# prep phase v2: next row pair's 26 loads issued before the current pair is processed (two register sets)
# speedup vs baseline: 1.0180x; 1.0074x over previous
; DI int get_tid() { int t = threadIdx.x; asm volatile("" : "+v"(t)); return t; }
; DI void prep_row_load(const Params& p, int row, const bf16_t* ur, int lane, PrepRow& R) {
;   {
;     const float2* csg = (const float2*)(p.ws + OFF_ROPEG);
;     const float2* csm = (const float2*)(p.ws + OFF_ROPEM);
;     const int s = row & 4095, d = lane & 31;
;     const int pg = (lane >> 5) ? (s & 63) : (s >> 6), pm = (d >> 4) ? (s & 63) : (s >> 6);
;     R.cs = csg[pg * 16 + (lane & 15)];
;     R.tm = csm[pm * 8 + (d & 7)];
;     if (row >= NLAT) { R.cs = make_float2(1.f, 0.f); R.tm = make_float2(1.f, 0.f); }
;   }
; #pragma unroll
;   for (int hd = 0; hd < 8; ++hd) R.hv[hd] = ur[768 + hd * 64 + lane];
;   R.mq = *(const uint2*)(ur + 1408 + lane * 4);
;   R.mkv = *(const unsigned*)(ur + 1664 + lane * 2);
;   R.kr = ur[1792 + (lane & 31)];
; }
; DI void prep_rows(const Params& p, int layer) {
;   const int lane = get_tid() & 63, gw = blockIdx.x * 4 + (get_tid() >> 6), nw = gridDim.x * 4;
;   const bf16_t* U = (const bf16_t*)(p.ws + OFF_U);
;   const float gq = p.gqa_q_g[layer * 64 + lane], gk = p.gqa_k_g[layer * 64 + lane];
;   const float4 g4 = *(const float4*)(p.mla_q_g + layer * 256 + lane * 4);
;   const float2 g2 = *(const float2*)(p.mla_kv_g + layer * 128 + lane * 2);
.Lpp_entry:
	v_writelane_b32 v254, s52, 0
	v_writelane_b32 v254, s53, 1
	v_writelane_b32 v254, s54, 2
	v_writelane_b32 v254, s55, 3
	v_writelane_b32 v254, s56, 4
	v_writelane_b32 v254, s57, 5
	v_writelane_b32 v254, s58, 6
	v_writelane_b32 v254, s59, 7
	v_writelane_b32 v254, s60, 8
	v_writelane_b32 v254, s61, 9
	v_writelane_b32 v254, s62, 10
	v_writelane_b32 v254, s63, 11
	v_writelane_b32 v254, s64, 12
	v_writelane_b32 v254, s65, 13
	v_writelane_b32 v254, s66, 14
	v_writelane_b32 v254, s67, 15
	v_writelane_b32 v254, s68, 16
	v_writelane_b32 v254, s69, 17
	v_writelane_b32 v254, s70, 18
	v_writelane_b32 v254, s71, 19
	v_writelane_b32 v254, s72, 20
	v_writelane_b32 v254, s73, 21
	v_writelane_b32 v254, s74, 22
	v_writelane_b32 v254, s75, 23
	v_writelane_b32 v254, s76, 24
	v_writelane_b32 v254, s77, 25
	v_writelane_b32 v254, s78, 26
	v_writelane_b32 v254, s79, 27
	v_writelane_b32 v254, s80, 28
	v_writelane_b32 v254, s81, 29
	v_writelane_b32 v254, s82, 30
	v_writelane_b32 v254, s83, 31
	v_writelane_b32 v254, s84, 32
	v_writelane_b32 v254, s85, 33
	v_writelane_b32 v254, s86, 34
	v_writelane_b32 v254, s87, 35
	v_writelane_b32 v254, s88, 36
	v_writelane_b32 v254, s89, 37
	v_writelane_b32 v254, s90, 38
	v_writelane_b32 v254, s91, 39
	s_mov_b32 s52, s101
	v_lshrrev_b32_e32 v32, 6, v143
	v_readlane_b32 s0, v255, 0
	s_nop 0
	v_readfirstlane_b32 s1, v32
	s_nop 3
	s_lshl_b32 s53, s0, 2
	s_add_u32 s53, s53, s1
	s_lshl_b32 s54, s26, 2
	v_readlane_b32 s56, v255, 1
	v_readlane_b32 s57, v255, 2
	s_nop 3
	s_load_dwordx2 s[10:11], s[56:57], 0x90
	s_load_dwordx2 s[12:13], s[56:57], 0x98
	s_load_dwordx2 s[28:29], s[56:57], 0xa0
	s_load_dwordx2 s[44:45], s[56:57], 0xa8
	v_and_b32_e32 v33, 63, v143
	v_lshl_add_u32 v34, s52, 6, v33
	v_lshlrev_b32_e32 v34, 2, v34
	v_lshlrev_b32_e32 v35, 4, v33
	s_lshl_b32 s0, s52, 10
	v_add_u32_e32 v35, s0, v35
	v_lshlrev_b32_e32 v36, 3, v33
	s_lshl_b32 s0, s52, 9
	v_add_u32_e32 v36, s0, v36
	s_waitcnt lgkmcnt(0)
	global_load_dword v213, v34, s[10:11]
	global_load_dword v214, v34, s[12:13]
	global_load_dwordx4 v[216:219], v35, s[28:29]
	global_load_dwordx2 v[220:221], v36, s[44:45]
	v_lshlrev_b32_e32 v222, 1, v33
	v_lshlrev_b32_e32 v223, 3, v33
	v_lshlrev_b32_e32 v224, 2, v33
	v_and_b32_e32 v37, 31, v33
	v_lshlrev_b32_e32 v225, 1, v37
	v_and_b32_e32 v38, 16, v33
	v_sub_u32_e32 v38, 16, v38
	v_lshlrev_b32_e32 v226, 27, v38
	v_and_b32_e32 v38, 8, v33
	v_sub_u32_e32 v38, 8, v38
	v_lshlrev_b32_e32 v227, 28, v38
	v_and_b32_e32 v38, 15, v33
	v_lshlrev_b32_e32 v228, 3, v38
	v_and_b32_e32 v38, 7, v33
	v_lshlrev_b32_e32 v229, 3, v38
	v_lshrrev_b32_e32 v233, 5, v33
	v_bfe_u32 v184, v33, 4, 1
	v_mul_u32_u24_e32 v38, 3, v233
	s_mov_b32 s0, 0xcc000
	v_mul_lo_u32 v38, v38, s0
	v_add_u32_e32 v230, v38, v225
	v_add_u32_e32 v230, 0x80, v230
	v_mov_b32_e32 v231, 0x358637bd
	v_mov_b32_e32 v232, 0x3e38aa3b
	s_waitcnt vmcnt(0)
	s_add_u32 s28, s24, 0x1e8d4000
	s_addc_u32 s29, s25, 0
	s_add_u32 s44, s24, 0x1e8d6000
	s_addc_u32 s45, s25, 0
	s_min_u32 s55, s53, 0x43ff
	s_lshl_b32 s13, s55, 1
	s_mul_i32 s0, s13, 3840
	s_add_u32 s46, s24, s0
	s_addc_u32 s47, s25, 0
	global_load_ushort v0, v222, s[46:47] offset:1536
	global_load_ushort v1, v222, s[46:47] offset:1664
	global_load_ushort v2, v222, s[46:47] offset:1792
	global_load_ushort v3, v222, s[46:47] offset:1920
	global_load_ushort v4, v222, s[46:47] offset:2048
	global_load_ushort v5, v222, s[46:47] offset:2176
	global_load_ushort v6, v222, s[46:47] offset:2304
	global_load_ushort v7, v222, s[46:47] offset:2432
	global_load_dwordx2 v[8:9], v223, s[46:47] offset:2816
	global_load_dword v14, v224, s[46:47] offset:3328
	global_load_ushort v17, v225, s[46:47] offset:3584
	s_cmp_lt_u32 s13, 0x8000
	s_cbranch_scc0 .Lpp_ctx_3
	s_and_b32 s1, s13, 0xfff
	s_lshr_b32 s11, s1, 6
	s_and_b32 s12, s1, 63
	s_sub_u32 s12, s12, s11
	v_mov_b32_e32 v32, s12
	v_mul_lo_u32 v36, v32, v233
	v_add_u32_e32 v36, s11, v36
	v_lshl_add_u32 v36, v36, 7, v228
	v_mul_lo_u32 v37, v32, v184
	v_add_u32_e32 v37, s11, v37
	v_lshl_add_u32 v37, v37, 6, v229
	global_load_dwordx2 v[18:19], v36, s[28:29]
	global_load_dwordx2 v[20:21], v37, s[44:45]
	s_branch .Lpp_j_4
.Lpp_ctx_3:
	v_mov_b32_e32 v36, 0
	global_load_dwordx2 v[18:19], v36, s[28:29]
	global_load_dwordx2 v[20:21], v36, s[44:45]
; DI void prep_row_load(const Params& p, int row, const bf16_t* ur, int lane, PrepRow& R) {
;   {
;     const float2* csg = (const float2*)(p.ws + OFF_ROPEG);
;     const float2* csm = (const float2*)(p.ws + OFF_ROPEM);
;     const int s = row & 4095, d = lane & 31;
;     const int pg = (lane >> 5) ? (s & 63) : (s >> 6), pm = (d >> 4) ? (s & 63) : (s >> 6);
;     R.cs = csg[pg * 16 + (lane & 15)];
;     R.tm = csm[pm * 8 + (d & 7)];
;     if (row >= NLAT) { R.cs = make_float2(1.f, 0.f); R.tm = make_float2(1.f, 0.f); }
;   }
; #pragma unroll
;   for (int hd = 0; hd < 8; ++hd) R.hv[hd] = ur[768 + hd * 64 + lane];
;   R.mq = *(const uint2*)(ur + 1408 + lane * 4);
;   R.mkv = *(const unsigned*)(ur + 1664 + lane * 2);
;   R.kr = ur[1792 + (lane & 31)];
; }
; DI void prep_rows(const Params& p, int layer) {
;     ...
;   for (int pr = gw; pr < (NTOK >> 1); pr += nw) {
;     const int row = pr * 2;
;     PrepRow Ra, Rb;
;     prep_row_load(p, row, U + (size_t)row * INP, lane, Ra);
;     prep_row_load(p, row + 1, U + (size_t)(row + 1) * INP, lane, Rb);
.Lpp_j_4:
	s_lshl_b32 s13, s55, 1
	s_add_u32 s13, s13, 1
	s_mul_i32 s0, s13, 3840
	s_add_u32 s46, s24, s0
	s_addc_u32 s47, s25, 0
	global_load_ushort v40, v222, s[46:47] offset:1536
	global_load_ushort v41, v222, s[46:47] offset:1664
	global_load_ushort v42, v222, s[46:47] offset:1792
	global_load_ushort v43, v222, s[46:47] offset:1920
	global_load_ushort v44, v222, s[46:47] offset:2048
	global_load_ushort v45, v222, s[46:47] offset:2176
	global_load_ushort v46, v222, s[46:47] offset:2304
	global_load_ushort v47, v222, s[46:47] offset:2432
	global_load_dwordx2 v[48:49], v223, s[46:47] offset:2816
	global_load_dword v54, v224, s[46:47] offset:3328
	global_load_ushort v57, v225, s[46:47] offset:3584
	s_cmp_lt_u32 s13, 0x8000
	s_cbranch_scc0 .Lpp_ctx_5
	s_and_b32 s1, s13, 0xfff
	s_lshr_b32 s11, s1, 6
	s_and_b32 s12, s1, 63
	s_sub_u32 s12, s12, s11
	v_mov_b32_e32 v72, s12
	v_mul_lo_u32 v76, v72, v233
	v_add_u32_e32 v76, s11, v76
	v_lshl_add_u32 v76, v76, 7, v228
	v_mul_lo_u32 v77, v72, v184
	v_add_u32_e32 v77, s11, v77
	v_lshl_add_u32 v77, v77, 6, v229
	global_load_dwordx2 v[58:59], v76, s[28:29]
	global_load_dwordx2 v[60:61], v77, s[44:45]
	s_branch .Lpp_j_6
.Lpp_ctx_5:
	v_mov_b32_e32 v76, 0
	global_load_dwordx2 v[58:59], v76, s[28:29]
	global_load_dwordx2 v[60:61], v76, s[44:45]
.Lpp_j_6:
	s_add_u32 s89, s53, s54
	s_min_u32 s55, s89, 0x43ff
	s_lshl_b32 s13, s55, 1
	s_mul_i32 s0, s13, 3840
	s_add_u32 s46, s24, s0
	s_addc_u32 s47, s25, 0
	global_load_ushort v80, v222, s[46:47] offset:1536
	global_load_ushort v81, v222, s[46:47] offset:1664
	global_load_ushort v82, v222, s[46:47] offset:1792
	global_load_ushort v83, v222, s[46:47] offset:1920
	global_load_ushort v84, v222, s[46:47] offset:2048
	global_load_ushort v85, v222, s[46:47] offset:2176
	global_load_ushort v86, v222, s[46:47] offset:2304
	global_load_ushort v87, v222, s[46:47] offset:2432
	global_load_dwordx2 v[88:89], v223, s[46:47] offset:2816
	global_load_dword v94, v224, s[46:47] offset:3328
	global_load_ushort v97, v225, s[46:47] offset:3584
	s_cmp_lt_u32 s13, 0x8000
	s_cbranch_scc0 .Lpp_ctx_7
	s_and_b32 s1, s13, 0xfff
	s_lshr_b32 s11, s1, 6
	s_and_b32 s12, s1, 63
	s_sub_u32 s12, s12, s11
	v_mov_b32_e32 v112, s12
	v_mul_lo_u32 v116, v112, v233
	v_add_u32_e32 v116, s11, v116
	v_lshl_add_u32 v116, v116, 7, v228
	v_mul_lo_u32 v117, v112, v184
	v_add_u32_e32 v117, s11, v117
	v_lshl_add_u32 v117, v117, 6, v229
	global_load_dwordx2 v[98:99], v116, s[28:29]
	global_load_dwordx2 v[100:101], v117, s[44:45]
	s_branch .Lpp_j_8
.Lpp_ctx_7:
	v_mov_b32_e32 v116, 0
	global_load_dwordx2 v[98:99], v116, s[28:29]
	global_load_dwordx2 v[100:101], v116, s[44:45]
.Lpp_j_8:
	s_lshl_b32 s13, s55, 1
	s_add_u32 s13, s13, 1
	s_mul_i32 s0, s13, 3840
	s_add_u32 s46, s24, s0
	s_addc_u32 s47, s25, 0
	global_load_ushort v144, v222, s[46:47] offset:1536
	global_load_ushort v145, v222, s[46:47] offset:1664
	global_load_ushort v146, v222, s[46:47] offset:1792
	global_load_ushort v147, v222, s[46:47] offset:1920
	global_load_ushort v148, v222, s[46:47] offset:2048
	global_load_ushort v149, v222, s[46:47] offset:2176
	global_load_ushort v150, v222, s[46:47] offset:2304
	global_load_ushort v151, v222, s[46:47] offset:2432
	global_load_dwordx2 v[152:153], v223, s[46:47] offset:2816
	global_load_dword v158, v224, s[46:47] offset:3328
	global_load_ushort v161, v225, s[46:47] offset:3584
	s_cmp_lt_u32 s13, 0x8000
	s_cbranch_scc0 .Lpp_ctx_9
	s_and_b32 s1, s13, 0xfff
	s_lshr_b32 s11, s1, 6
	s_and_b32 s12, s1, 63
	s_sub_u32 s12, s12, s11
	v_mov_b32_e32 v176, s12
	v_mul_lo_u32 v180, v176, v233
	v_add_u32_e32 v180, s11, v180
	v_lshl_add_u32 v180, v180, 7, v228
	v_mul_lo_u32 v181, v176, v184
	v_add_u32_e32 v181, s11, v181
	v_lshl_add_u32 v181, v181, 6, v229
	global_load_dwordx2 v[162:163], v180, s[28:29]
	global_load_dwordx2 v[164:165], v181, s[44:45]
	s_branch .Lpp_j_10
.Lpp_ctx_9:
	v_mov_b32_e32 v180, 0
	global_load_dwordx2 v[162:163], v180, s[28:29]
	global_load_dwordx2 v[164:165], v180, s[44:45]
.Lpp_j_10:
.Lpp_loop_1:
	s_lshl_b32 s70, s53, 1
	s_cmp_lt_u32 s70, 0x8000
	s_cbranch_scc0 .Lpp_cctx_11
	s_lshr_b32 s0, s70, 12
	s_and_b32 s10, s70, 0xfff
	s_add_u32 s10, s10, 256
	s_branch .Lpp_cj_12

; DI void prep_row_store(const Params& p, int layer, int row, int lane, const PrepRow& R, float gq, float gk, float4 g4, float2 g2) {
;   bf16_t* Qg = (bf16_t*)(p.ws + OFF_QG);
;   bf16_t* Kg = (bf16_t*)(p.ws + OFF_KG);
;   bf16_t* Km = (bf16_t*)(p.ws + OFF_KM);
;   bf16_t* MQN = (bf16_t*)(p.ws + OFF_MQN);
;   bf16_t* MKVN = (bf16_t*)(p.ws + OFF_MKVN);
;   const float qs = 0.125f * LOG2E;
;   int b, kp; row_info(row, b, kp);
;   const bool lat = row < NLAT;
.Lpp_cj_12:
	s_mul_i32 s11, s0, 26112
	s_add_u32 s11, s11, s10
	s_lshl_b32 s12, s11, 7
	s_add_u32 s12, s12, 0x7f80000
	s_add_u32 s60, s24, s12
	s_addc_u32 s61, s25, 0
	s_mul_i32 s12, s11, 192
	s_add_u32 s12, s12, 0xd040000
	s_add_u32 s68, s24, s12
	s_addc_u32 s69, s25, 0
	s_mul_i32 s11, s0, 8704
	s_add_u32 s11, s11, s10
	s_lshl_b32 s12, s11, 7
	s_add_u32 s12, s12, 0x9900000
	s_add_u32 s62, s24, s12
	s_addc_u32 s63, s25, 0
	s_lshl_b32 s12, s70, 9
	s_add_u32 s12, s12, 0x11000000
	s_add_u32 s64, s24, s12
	s_addc_u32 s65, s25, 0
	s_lshl_b32 s12, s70, 8
	s_add_u32 s12, s12, 0x12100000
	s_add_u32 s66, s24, s12
	s_addc_u32 s67, s25, 0
	s_lshl_b32 s86, s53, 1
	s_add_u32 s86, s86, 1
	s_cmp_lt_u32 s86, 0x8000
	s_cbranch_scc0 .Lpp_cctx_13
	s_lshr_b32 s0, s86, 12
	s_and_b32 s10, s86, 0xfff
	s_add_u32 s10, s10, 256
	s_branch .Lpp_cj_14

; DI unsigned pack2(float lo, float hi) { f32x2_t v = {lo, hi}; bf16x2_t r = __builtin_convertvector(v, bf16x2_t); return __builtin_bit_cast(unsigned, r); }
; DI bf16_t f2bf(float x) { return (bf16_t)(pack2(x, x) & 0xffffu); }
; DI float bf2f(bf16_t v) { return __uint_as_float(((unsigned)v) << 16); }
; DI void prep_row_store(const Params& p, int layer, int row, int lane, const PrepRow& R, float gq, float gk, float4 g4, float2 g2) {
;     ...
;     float xv = bf2f(R.hv[hd]);
;     float ss = wave_sum(xv * xv);
;     float y = xv * rsqrtf(ss * (1.0f / 64.f) + 1e-6f) * (hd < 6 ? gq : gk);
;     float pv = __shfl_xor(y, 16);
;     float o = y * cs_c + (upper ? pv : -pv) * cs_s;
;     if (hd < 6) Qg[((size_t)(b * 6 + hd) * NKEY + kp) * 64 + lane] = f2bf(o * qs);
;     else Kg[((size_t)(b * 2 + (hd - 6)) * NKEY + kp) * 64 + lane] = f2bf(o);
;   }
;   {
;     const uint2 w = R.mq;
;     float x0 = bf2f((bf16_t)(w.x & 0xffff)), x1 = bf2f((bf16_t)(w.x >> 16)), x2 = bf2f((bf16_t)(w.y & 0xffff)), x3 = bf2f((bf16_t)(w.y >> 16));
;     float ss = wave_sum(x0 * x0 + x1 * x1 + x2 * x2 + x3 * x3);
;     float rstd = rsqrtf(ss * (1.0f / 256.f) + 1e-6f);
;     uint2 o; o.x = pack2(x0 * rstd * g4.x, x1 * rstd * g4.y); o.y = pack2(x2 * rstd * g4.z, x3 * rstd * g4.w);
;     *(uint2*)(MQN + (size_t)row * 256 + lane * 4) = o;
;   }
;   {
;     const unsigned w = R.mkv;
;     float x0 = bf2f((bf16_t)(w & 0xffff)), x1 = bf2f((bf16_t)(w >> 16));
;     float ss = wave_sum(x0 * x0 + x1 * x1);
.Lpp_cj_14:
	s_mul_i32 s11, s0, 26112
	s_add_u32 s11, s11, s10
	s_lshl_b32 s12, s11, 7
	s_add_u32 s12, s12, 0x7f80000
	s_add_u32 s76, s24, s12
	s_addc_u32 s77, s25, 0
	s_mul_i32 s12, s11, 192
	s_add_u32 s12, s12, 0xd040000
	s_add_u32 s84, s24, s12
	s_addc_u32 s85, s25, 0
	s_mul_i32 s11, s0, 8704
	s_add_u32 s11, s11, s10
	s_lshl_b32 s12, s11, 7
	s_add_u32 s12, s12, 0x9900000
	s_add_u32 s78, s24, s12
	s_addc_u32 s79, s25, 0
	s_lshl_b32 s12, s86, 9
	s_add_u32 s12, s12, 0x11000000
	s_add_u32 s80, s24, s12
	s_addc_u32 s81, s25, 0
	s_lshl_b32 s12, s86, 8
	s_add_u32 s12, s12, 0x12100000
	s_add_u32 s82, s24, s12
	s_addc_u32 s83, s25, 0
	s_waitcnt vmcnt(39)
	v_lshlrev_b32_e32 v0, 16, v0
	v_lshlrev_b32_e32 v1, 16, v1
	v_lshlrev_b32_e32 v2, 16, v2
	v_lshlrev_b32_e32 v3, 16, v3
	v_lshlrev_b32_e32 v4, 16, v4
	v_lshlrev_b32_e32 v5, 16, v5
	v_lshlrev_b32_e32 v6, 16, v6
	v_lshlrev_b32_e32 v7, 16, v7
	v_lshlrev_b32_e32 v10, 16, v8
	v_and_b32_e32 v11, 0xffff0000, v8
	v_lshlrev_b32_e32 v12, 16, v9
	v_and_b32_e32 v13, 0xffff0000, v9
	v_lshlrev_b32_e32 v15, 16, v14
	v_and_b32_e32 v16, 0xffff0000, v14
	v_lshlrev_b32_e32 v17, 16, v17
	v_mul_f32_e32 v22, v0, v0
	v_mul_f32_e32 v23, v1, v1
	v_mul_f32_e32 v24, v2, v2
	v_mul_f32_e32 v25, v3, v3
	v_mul_f32_e32 v26, v4, v4
	v_mul_f32_e32 v27, v5, v5
	v_mul_f32_e32 v28, v6, v6
	v_mul_f32_e32 v29, v7, v7
	v_mul_f32_e32 v30, v10, v10
	v_fmac_f32_e32 v30, v11, v11
	v_fmac_f32_e32 v30, v12, v12
	v_fmac_f32_e32 v30, v13, v13
	v_mul_f32_e32 v31, v15, v15
	v_fmac_f32_e32 v31, v16, v16
	s_waitcnt vmcnt(26)
	v_lshlrev_b32_e32 v40, 16, v40
	v_lshlrev_b32_e32 v41, 16, v41
	v_lshlrev_b32_e32 v42, 16, v42
	v_lshlrev_b32_e32 v43, 16, v43
	v_lshlrev_b32_e32 v44, 16, v44
	v_lshlrev_b32_e32 v45, 16, v45
	v_lshlrev_b32_e32 v46, 16, v46
	v_lshlrev_b32_e32 v47, 16, v47
	v_lshlrev_b32_e32 v50, 16, v48
	v_and_b32_e32 v51, 0xffff0000, v48
	v_lshlrev_b32_e32 v52, 16, v49
	v_and_b32_e32 v53, 0xffff0000, v49
	v_lshlrev_b32_e32 v55, 16, v54
	v_and_b32_e32 v56, 0xffff0000, v54
	v_lshlrev_b32_e32 v57, 16, v57
	v_mul_f32_e32 v62, v40, v40
	v_mul_f32_e32 v63, v41, v41
	v_mul_f32_e32 v64, v42, v42
	v_mul_f32_e32 v65, v43, v43
	v_mul_f32_e32 v66, v44, v44
	v_mul_f32_e32 v67, v45, v45
	v_mul_f32_e32 v68, v46, v46
	v_mul_f32_e32 v69, v47, v47
	v_mul_f32_e32 v70, v50, v50
	v_fmac_f32_e32 v70, v51, v51
	v_fmac_f32_e32 v70, v52, v52
	v_fmac_f32_e32 v70, v53, v53
	v_mul_f32_e32 v71, v55, v55
	v_fmac_f32_e32 v71, v56, v56
	v_add_f32_dpp v22, v22, v22 quad_perm:[1,0,3,2] row_mask:0xf bank_mask:0xf
	v_add_f32_dpp v23, v23, v23 quad_perm:[1,0,3,2] row_mask:0xf bank_mask:0xf
	v_add_f32_dpp v24, v24, v24 quad_perm:[1,0,3,2] row_mask:0xf bank_mask:0xf
	v_add_f32_dpp v25, v25, v25 quad_perm:[1,0,3,2] row_mask:0xf bank_mask:0xf
	v_add_f32_dpp v26, v26, v26 quad_perm:[1,0,3,2] row_mask:0xf bank_mask:0xf
	v_add_f32_dpp v27, v27, v27 quad_perm:[1,0,3,2] row_mask:0xf bank_mask:0xf
	v_add_f32_dpp v28, v28, v28 quad_perm:[1,0,3,2] row_mask:0xf bank_mask:0xf
	v_add_f32_dpp v29, v29, v29 quad_perm:[1,0,3,2] row_mask:0xf bank_mask:0xf
	v_add_f32_dpp v30, v30, v30 quad_perm:[1,0,3,2] row_mask:0xf bank_mask:0xf
	v_add_f32_dpp v31, v31, v31 quad_perm:[1,0,3,2] row_mask:0xf bank_mask:0xf
	v_add_f32_dpp v62, v62, v62 quad_perm:[1,0,3,2] row_mask:0xf bank_mask:0xf
	v_add_f32_dpp v63, v63, v63 quad_perm:[1,0,3,2] row_mask:0xf bank_mask:0xf
	v_add_f32_dpp v64, v64, v64 quad_perm:[1,0,3,2] row_mask:0xf bank_mask:0xf
	v_add_f32_dpp v65, v65, v65 quad_perm:[1,0,3,2] row_mask:0xf bank_mask:0xf
	v_add_f32_dpp v66, v66, v66 quad_perm:[1,0,3,2] row_mask:0xf bank_mask:0xf
	v_add_f32_dpp v67, v67, v67 quad_perm:[1,0,3,2] row_mask:0xf bank_mask:0xf
	v_add_f32_dpp v68, v68, v68 quad_perm:[1,0,3,2] row_mask:0xf bank_mask:0xf
	v_add_f32_dpp v69, v69, v69 quad_perm:[1,0,3,2] row_mask:0xf bank_mask:0xf
	v_add_f32_dpp v70, v70, v70 quad_perm:[1,0,3,2] row_mask:0xf bank_mask:0xf
	v_add_f32_dpp v71, v71, v71 quad_perm:[1,0,3,2] row_mask:0xf bank_mask:0xf
	v_add_f32_dpp v22, v22, v22 quad_perm:[2,3,0,1] row_mask:0xf bank_mask:0xf
	v_add_f32_dpp v23, v23, v23 quad_perm:[2,3,0,1] row_mask:0xf bank_mask:0xf
	v_add_f32_dpp v24, v24, v24 quad_perm:[2,3,0,1] row_mask:0xf bank_mask:0xf
	v_add_f32_dpp v25, v25, v25 quad_perm:[2,3,0,1] row_mask:0xf bank_mask:0xf
	v_add_f32_dpp v26, v26, v26 quad_perm:[2,3,0,1] row_mask:0xf bank_mask:0xf
	v_add_f32_dpp v27, v27, v27 quad_perm:[2,3,0,1] row_mask:0xf bank_mask:0xf
	v_add_f32_dpp v28, v28, v28 quad_perm:[2,3,0,1] row_mask:0xf bank_mask:0xf
	v_add_f32_dpp v29, v29, v29 quad_perm:[2,3,0,1] row_mask:0xf bank_mask:0xf
	v_add_f32_dpp v30, v30, v30 quad_perm:[2,3,0,1] row_mask:0xf bank_mask:0xf
	v_add_f32_dpp v31, v31, v31 quad_perm:[2,3,0,1] row_mask:0xf bank_mask:0xf
	v_add_f32_dpp v62, v62, v62 quad_perm:[2,3,0,1] row_mask:0xf bank_mask:0xf
	v_add_f32_dpp v63, v63, v63 quad_perm:[2,3,0,1] row_mask:0xf bank_mask:0xf
	v_add_f32_dpp v64, v64, v64 quad_perm:[2,3,0,1] row_mask:0xf bank_mask:0xf
	v_add_f32_dpp v65, v65, v65 quad_perm:[2,3,0,1] row_mask:0xf bank_mask:0xf
	v_add_f32_dpp v66, v66, v66 quad_perm:[2,3,0,1] row_mask:0xf bank_mask:0xf
	v_add_f32_dpp v67, v67, v67 quad_perm:[2,3,0,1] row_mask:0xf bank_mask:0xf
	v_add_f32_dpp v68, v68, v68 quad_perm:[2,3,0,1] row_mask:0xf bank_mask:0xf
	v_add_f32_dpp v69, v69, v69 quad_perm:[2,3,0,1] row_mask:0xf bank_mask:0xf
	v_add_f32_dpp v70, v70, v70 quad_perm:[2,3,0,1] row_mask:0xf bank_mask:0xf
	v_add_f32_dpp v71, v71, v71 quad_perm:[2,3,0,1] row_mask:0xf bank_mask:0xf
	v_add_f32_dpp v22, v22, v22 row_half_mirror row_mask:0xf bank_mask:0xf
	v_add_f32_dpp v23, v23, v23 row_half_mirror row_mask:0xf bank_mask:0xf
; DI unsigned pack2(float lo, float hi) { f32x2_t v = {lo, hi}; bf16x2_t r = __builtin_convertvector(v, bf16x2_t); return __builtin_bit_cast(unsigned, r); }
; DI bf16_t f2bf(float x) { return (bf16_t)(pack2(x, x) & 0xffffu); }
; DI float bf2f(bf16_t v) { return __uint_as_float(((unsigned)v) << 16); }
; DI float wave_sum(float v) {
; #pragma unroll
;   for (int o = 32; o > 0; o >>= 1) v += __shfl_xor(v, o);
;   return v;
; DI void prep_row_store(const Params& p, int layer, int row, int lane, const PrepRow& R, float gq, float gk, float4 g4, float2 g2) {
;     ...
;     float xv = bf2f(R.hv[hd]);
;     float ss = wave_sum(xv * xv);
;     float y = xv * rsqrtf(ss * (1.0f / 64.f) + 1e-6f) * (hd < 6 ? gq : gk);
;     float pv = __shfl_xor(y, 16);
;     float o = y * cs_c + (upper ? pv : -pv) * cs_s;
;     if (hd < 6) Qg[((size_t)(b * 6 + hd) * NKEY + kp) * 64 + lane] = f2bf(o * qs);
;     else Kg[((size_t)(b * 2 + (hd - 6)) * NKEY + kp) * 64 + lane] = f2bf(o);
;   }
;   {
;     const uint2 w = R.mq;
;     float x0 = bf2f((bf16_t)(w.x & 0xffff)), x1 = bf2f((bf16_t)(w.x >> 16)), x2 = bf2f((bf16_t)(w.y & 0xffff)), x3 = bf2f((bf16_t)(w.y >> 16));
;     float ss = wave_sum(x0 * x0 + x1 * x1 + x2 * x2 + x3 * x3);
;     float rstd = rsqrtf(ss * (1.0f / 256.f) + 1e-6f);
;     uint2 o; o.x = pack2(x0 * rstd * g4.x, x1 * rstd * g4.y); o.y = pack2(x2 * rstd * g4.z, x3 * rstd * g4.w);
;     *(uint2*)(MQN + (size_t)row * 256 + lane * 4) = o;
;   }
;   {
;     const unsigned w = R.mkv;
;     float x0 = bf2f((bf16_t)(w & 0xffff)), x1 = bf2f((bf16_t)(w >> 16));
;     float ss = wave_sum(x0 * x0 + x1 * x1);
;     float rstd = rsqrtf(ss * (1.0f / 128.f) + 1e-6f);
	v_add_f32_dpp v24, v24, v24 row_half_mirror row_mask:0xf bank_mask:0xf
	v_add_f32_dpp v25, v25, v25 row_half_mirror row_mask:0xf bank_mask:0xf
	v_add_f32_dpp v26, v26, v26 row_half_mirror row_mask:0xf bank_mask:0xf
	v_add_f32_dpp v27, v27, v27 row_half_mirror row_mask:0xf bank_mask:0xf
	v_add_f32_dpp v28, v28, v28 row_half_mirror row_mask:0xf bank_mask:0xf
	v_add_f32_dpp v29, v29, v29 row_half_mirror row_mask:0xf bank_mask:0xf
	v_add_f32_dpp v30, v30, v30 row_half_mirror row_mask:0xf bank_mask:0xf
	v_add_f32_dpp v31, v31, v31 row_half_mirror row_mask:0xf bank_mask:0xf
	v_add_f32_dpp v62, v62, v62 row_half_mirror row_mask:0xf bank_mask:0xf
	v_add_f32_dpp v63, v63, v63 row_half_mirror row_mask:0xf bank_mask:0xf
	v_add_f32_dpp v64, v64, v64 row_half_mirror row_mask:0xf bank_mask:0xf
	v_add_f32_dpp v65, v65, v65 row_half_mirror row_mask:0xf bank_mask:0xf
	v_add_f32_dpp v66, v66, v66 row_half_mirror row_mask:0xf bank_mask:0xf
	v_add_f32_dpp v67, v67, v67 row_half_mirror row_mask:0xf bank_mask:0xf
	v_add_f32_dpp v68, v68, v68 row_half_mirror row_mask:0xf bank_mask:0xf
	v_add_f32_dpp v69, v69, v69 row_half_mirror row_mask:0xf bank_mask:0xf
	v_add_f32_dpp v70, v70, v70 row_half_mirror row_mask:0xf bank_mask:0xf
	v_add_f32_dpp v71, v71, v71 row_half_mirror row_mask:0xf bank_mask:0xf
	v_add_f32_dpp v22, v22, v22 row_mirror row_mask:0xf bank_mask:0xf
	v_add_f32_dpp v23, v23, v23 row_mirror row_mask:0xf bank_mask:0xf
	v_add_f32_dpp v24, v24, v24 row_mirror row_mask:0xf bank_mask:0xf
	v_add_f32_dpp v25, v25, v25 row_mirror row_mask:0xf bank_mask:0xf
	v_add_f32_dpp v26, v26, v26 row_mirror row_mask:0xf bank_mask:0xf
	v_add_f32_dpp v27, v27, v27 row_mirror row_mask:0xf bank_mask:0xf
	v_add_f32_dpp v28, v28, v28 row_mirror row_mask:0xf bank_mask:0xf
	v_add_f32_dpp v29, v29, v29 row_mirror row_mask:0xf bank_mask:0xf
	v_add_f32_dpp v30, v30, v30 row_mirror row_mask:0xf bank_mask:0xf
	v_add_f32_dpp v31, v31, v31 row_mirror row_mask:0xf bank_mask:0xf
	v_add_f32_dpp v62, v62, v62 row_mirror row_mask:0xf bank_mask:0xf
	v_add_f32_dpp v63, v63, v63 row_mirror row_mask:0xf bank_mask:0xf
	v_add_f32_dpp v64, v64, v64 row_mirror row_mask:0xf bank_mask:0xf
	v_add_f32_dpp v65, v65, v65 row_mirror row_mask:0xf bank_mask:0xf
	v_add_f32_dpp v66, v66, v66 row_mirror row_mask:0xf bank_mask:0xf
	v_add_f32_dpp v67, v67, v67 row_mirror row_mask:0xf bank_mask:0xf
	v_add_f32_dpp v68, v68, v68 row_mirror row_mask:0xf bank_mask:0xf
	v_add_f32_dpp v69, v69, v69 row_mirror row_mask:0xf bank_mask:0xf
	v_add_f32_dpp v70, v70, v70 row_mirror row_mask:0xf bank_mask:0xf
	v_add_f32_dpp v71, v71, v71 row_mirror row_mask:0xf bank_mask:0xf
	s_nop 1
	v_readlane_b32 s90, v22, 0
	v_readlane_b32 s91, v22, 16
	v_readlane_b32 s72, v22, 32
	v_readlane_b32 s73, v22, 48
	s_nop 1
	v_mov_b32_e32 v22, s90
	v_add_f32_e32 v22, s91, v22
	v_add_f32_e32 v22, s72, v22
	v_add_f32_e32 v22, s73, v22
	v_readlane_b32 s90, v23, 0
	v_readlane_b32 s91, v23, 16
	v_readlane_b32 s72, v23, 32
	v_readlane_b32 s73, v23, 48
	s_nop 1
	v_mov_b32_e32 v23, s90
	v_add_f32_e32 v23, s91, v23
	v_add_f32_e32 v23, s72, v23
	v_add_f32_e32 v23, s73, v23
	v_readlane_b32 s90, v24, 0
	v_readlane_b32 s91, v24, 16
	v_readlane_b32 s72, v24, 32
	v_readlane_b32 s73, v24, 48
	s_nop 1
	v_mov_b32_e32 v24, s90
	v_add_f32_e32 v24, s91, v24
	v_add_f32_e32 v24, s72, v24
	v_add_f32_e32 v24, s73, v24
	v_readlane_b32 s90, v25, 0
	v_readlane_b32 s91, v25, 16
	v_readlane_b32 s72, v25, 32
	v_readlane_b32 s73, v25, 48
	s_nop 1
	v_mov_b32_e32 v25, s90
	v_add_f32_e32 v25, s91, v25
	v_add_f32_e32 v25, s72, v25
	v_add_f32_e32 v25, s73, v25
	v_readlane_b32 s90, v26, 0
	v_readlane_b32 s91, v26, 16
	v_readlane_b32 s72, v26, 32
	v_readlane_b32 s73, v26, 48
	s_nop 1
	v_mov_b32_e32 v26, s90
	v_add_f32_e32 v26, s91, v26
	v_add_f32_e32 v26, s72, v26
	v_add_f32_e32 v26, s73, v26
	v_readlane_b32 s90, v27, 0
	v_readlane_b32 s91, v27, 16
	v_readlane_b32 s72, v27, 32
	v_readlane_b32 s73, v27, 48
	s_nop 1
	v_mov_b32_e32 v27, s90
	v_add_f32_e32 v27, s91, v27
	v_add_f32_e32 v27, s72, v27
	v_add_f32_e32 v27, s73, v27
	v_readlane_b32 s90, v28, 0
	v_readlane_b32 s91, v28, 16
	v_readlane_b32 s72, v28, 32
	v_readlane_b32 s73, v28, 48
	s_nop 1
	v_mov_b32_e32 v28, s90
	v_add_f32_e32 v28, s91, v28
	v_add_f32_e32 v28, s72, v28
	v_add_f32_e32 v28, s73, v28
	v_readlane_b32 s90, v29, 0
	v_readlane_b32 s91, v29, 16
	v_readlane_b32 s72, v29, 32
	v_readlane_b32 s73, v29, 48
	s_nop 1
	v_mov_b32_e32 v29, s90
	v_add_f32_e32 v29, s91, v29
	v_add_f32_e32 v29, s72, v29
	v_add_f32_e32 v29, s73, v29
	v_readlane_b32 s90, v30, 0
	v_readlane_b32 s91, v30, 16
	v_readlane_b32 s72, v30, 32
	v_readlane_b32 s73, v30, 48
	s_nop 1
	v_mov_b32_e32 v30, s90
	v_add_f32_e32 v30, s91, v30
	v_add_f32_e32 v30, s72, v30
	v_add_f32_e32 v30, s73, v30
	v_readlane_b32 s90, v31, 0
	v_readlane_b32 s91, v31, 16
	v_readlane_b32 s72, v31, 32
	v_readlane_b32 s73, v31, 48
	s_nop 1
	v_mov_b32_e32 v31, s90
	v_add_f32_e32 v31, s91, v31
	v_add_f32_e32 v31, s72, v31
	v_add_f32_e32 v31, s73, v31
	v_readlane_b32 s90, v62, 0
	v_readlane_b32 s91, v62, 16
	v_readlane_b32 s72, v62, 32
	v_readlane_b32 s73, v62, 48
	s_nop 1
	v_mov_b32_e32 v62, s90
	v_add_f32_e32 v62, s91, v62
	v_add_f32_e32 v62, s72, v62
	v_add_f32_e32 v62, s73, v62
	v_readlane_b32 s90, v63, 0
	v_readlane_b32 s91, v63, 16
	v_readlane_b32 s72, v63, 32
	v_readlane_b32 s73, v63, 48
	s_nop 1
	v_mov_b32_e32 v63, s90
	v_add_f32_e32 v63, s91, v63
	v_add_f32_e32 v63, s72, v63
	v_add_f32_e32 v63, s73, v63
	v_readlane_b32 s90, v64, 0
	v_readlane_b32 s91, v64, 16
	v_readlane_b32 s72, v64, 32
	v_readlane_b32 s73, v64, 48
	s_nop 1
	v_mov_b32_e32 v64, s90
	v_add_f32_e32 v64, s91, v64
; DI unsigned pack2(float lo, float hi) { f32x2_t v = {lo, hi}; bf16x2_t r = __builtin_convertvector(v, bf16x2_t); return __builtin_bit_cast(unsigned, r); }
; DI bf16_t f2bf(float x) { return (bf16_t)(pack2(x, x) & 0xffffu); }
; DI float bf2f(bf16_t v) { return __uint_as_float(((unsigned)v) << 16); }
; DI void prep_row_store(const Params& p, int layer, int row, int lane, const PrepRow& R, float gq, float gk, float4 g4, float2 g2) {
;     ...
;     float xv = bf2f(R.hv[hd]);
;     float ss = wave_sum(xv * xv);
;     float y = xv * rsqrtf(ss * (1.0f / 64.f) + 1e-6f) * (hd < 6 ? gq : gk);
;     float pv = __shfl_xor(y, 16);
;     float o = y * cs_c + (upper ? pv : -pv) * cs_s;
;     if (hd < 6) Qg[((size_t)(b * 6 + hd) * NKEY + kp) * 64 + lane] = f2bf(o * qs);
;     else Kg[((size_t)(b * 2 + (hd - 6)) * NKEY + kp) * 64 + lane] = f2bf(o);
;   }
;   {
;     const uint2 w = R.mq;
;     float x0 = bf2f((bf16_t)(w.x & 0xffff)), x1 = bf2f((bf16_t)(w.x >> 16)), x2 = bf2f((bf16_t)(w.y & 0xffff)), x3 = bf2f((bf16_t)(w.y >> 16));
;     float ss = wave_sum(x0 * x0 + x1 * x1 + x2 * x2 + x3 * x3);
;     float rstd = rsqrtf(ss * (1.0f / 256.f) + 1e-6f);
;     uint2 o; o.x = pack2(x0 * rstd * g4.x, x1 * rstd * g4.y); o.y = pack2(x2 * rstd * g4.z, x3 * rstd * g4.w);
;     *(uint2*)(MQN + (size_t)row * 256 + lane * 4) = o;
;   }
;   {
;     const unsigned w = R.mkv;
;     float x0 = bf2f((bf16_t)(w & 0xffff)), x1 = bf2f((bf16_t)(w >> 16));
;     float ss = wave_sum(x0 * x0 + x1 * x1);
;     float rstd = rsqrtf(ss * (1.0f / 128.f) + 1e-6f);
;     *(unsigned*)(MKVN + (size_t)row * 128 + lane * 2) = pack2(x0 * rstd * g2.x, x1 * rstd * g2.y);
;   }
;   {
;     int d = lane & 31;
;     float xv = bf2f(R.kr);
;     float pv = __shfl_xor(xv, 8);
;     float o = lat ? (xv * tm.x + ((d & 8) ? pv : -pv) * tm.y) : xv;
;     bf16_t ob = f2bf(o);
;     int hb = (lane >> 5) * 3;
; #pragma unroll
;     for (int hh = 0; hh < 3; ++hh) Km[((size_t)(b * 6 + hb + hh) * NKEY + kp) * 96 + 64 + d] = ob;
;   }
	v_add_f32_e32 v64, s72, v64
	v_add_f32_e32 v64, s73, v64
	v_readlane_b32 s90, v65, 0
	v_readlane_b32 s91, v65, 16
	v_readlane_b32 s72, v65, 32
	v_readlane_b32 s73, v65, 48
	s_nop 1
	v_mov_b32_e32 v65, s90
	v_add_f32_e32 v65, s91, v65
	v_add_f32_e32 v65, s72, v65
	v_add_f32_e32 v65, s73, v65
	v_readlane_b32 s90, v66, 0
	v_readlane_b32 s91, v66, 16
	v_readlane_b32 s72, v66, 32
	v_readlane_b32 s73, v66, 48
	s_nop 1
	v_mov_b32_e32 v66, s90
	v_add_f32_e32 v66, s91, v66
	v_add_f32_e32 v66, s72, v66
	v_add_f32_e32 v66, s73, v66
	v_readlane_b32 s90, v67, 0
	v_readlane_b32 s91, v67, 16
	v_readlane_b32 s72, v67, 32
	v_readlane_b32 s73, v67, 48
	s_nop 1
	v_mov_b32_e32 v67, s90
	v_add_f32_e32 v67, s91, v67
	v_add_f32_e32 v67, s72, v67
	v_add_f32_e32 v67, s73, v67
	v_readlane_b32 s90, v68, 0
	v_readlane_b32 s91, v68, 16
	v_readlane_b32 s72, v68, 32
	v_readlane_b32 s73, v68, 48
	s_nop 1
	v_mov_b32_e32 v68, s90
	v_add_f32_e32 v68, s91, v68
	v_add_f32_e32 v68, s72, v68
	v_add_f32_e32 v68, s73, v68
	v_readlane_b32 s90, v69, 0
	v_readlane_b32 s91, v69, 16
	v_readlane_b32 s72, v69, 32
	v_readlane_b32 s73, v69, 48
	s_nop 1
	v_mov_b32_e32 v69, s90
	v_add_f32_e32 v69, s91, v69
	v_add_f32_e32 v69, s72, v69
	v_add_f32_e32 v69, s73, v69
	v_readlane_b32 s90, v70, 0
	v_readlane_b32 s91, v70, 16
	v_readlane_b32 s72, v70, 32
	v_readlane_b32 s73, v70, 48
	s_nop 1
	v_mov_b32_e32 v70, s90
	v_add_f32_e32 v70, s91, v70
	v_add_f32_e32 v70, s72, v70
	v_add_f32_e32 v70, s73, v70
	v_readlane_b32 s90, v71, 0
	v_readlane_b32 s91, v71, 16
	v_readlane_b32 s72, v71, 32
	v_readlane_b32 s73, v71, 48
	s_nop 1
	v_mov_b32_e32 v71, s90
	v_add_f32_e32 v71, s91, v71
	v_add_f32_e32 v71, s72, v71
	v_add_f32_e32 v71, s73, v71
	s_mov_b32 s0, 0x3c800000
	s_mov_b32 s1, 0x3b800000
	s_mov_b32 s10, 0x3c000000
	v_fma_f32 v22, v22, s0, v231
	v_fma_f32 v23, v23, s0, v231
	v_fma_f32 v24, v24, s0, v231
	v_fma_f32 v25, v25, s0, v231
	v_fma_f32 v26, v26, s0, v231
	v_fma_f32 v27, v27, s0, v231
	v_fma_f32 v28, v28, s0, v231
	v_fma_f32 v29, v29, s0, v231
	v_fma_f32 v30, v30, s1, v231
	v_fma_f32 v31, v31, s10, v231
	v_rsq_f32_e32 v22, v22
	v_rsq_f32_e32 v23, v23
	v_rsq_f32_e32 v24, v24
	v_rsq_f32_e32 v25, v25
	v_rsq_f32_e32 v26, v26
	v_rsq_f32_e32 v27, v27
	v_rsq_f32_e32 v28, v28
	v_rsq_f32_e32 v29, v29
	v_rsq_f32_e32 v30, v30
	v_rsq_f32_e32 v31, v31
	v_fma_f32 v62, v62, s0, v231
	v_fma_f32 v63, v63, s0, v231
	v_fma_f32 v64, v64, s0, v231
	v_fma_f32 v65, v65, s0, v231
	v_fma_f32 v66, v66, s0, v231
	v_fma_f32 v67, v67, s0, v231
	v_fma_f32 v68, v68, s0, v231
	v_fma_f32 v69, v69, s0, v231
	v_fma_f32 v70, v70, s1, v231
	v_fma_f32 v71, v71, s10, v231
	v_rsq_f32_e32 v62, v62
	v_rsq_f32_e32 v63, v63
	v_rsq_f32_e32 v64, v64
	v_rsq_f32_e32 v65, v65
	v_rsq_f32_e32 v66, v66
	v_rsq_f32_e32 v67, v67
	v_rsq_f32_e32 v68, v68
	v_rsq_f32_e32 v69, v69
	v_rsq_f32_e32 v70, v70
	v_rsq_f32_e32 v71, v71
	v_mul_f32_e32 v0, v0, v22
	v_mul_f32_e32 v1, v1, v23
	v_mul_f32_e32 v2, v2, v24
	v_mul_f32_e32 v3, v3, v25
	v_mul_f32_e32 v4, v4, v26
	v_mul_f32_e32 v5, v5, v27
	v_mul_f32_e32 v6, v6, v28
	v_mul_f32_e32 v7, v7, v29
	v_mul_f32_e32 v0, v0, v213
	v_mul_f32_e32 v1, v1, v213
	v_mul_f32_e32 v2, v2, v213
	v_mul_f32_e32 v3, v3, v213
	v_mul_f32_e32 v4, v4, v213
	v_mul_f32_e32 v5, v5, v213
	v_mul_f32_e32 v6, v6, v214
	v_mul_f32_e32 v7, v7, v214
	ds_swizzle_b32 v22, v0 offset:0x401f
	ds_swizzle_b32 v23, v1 offset:0x401f
	ds_swizzle_b32 v24, v2 offset:0x401f
	ds_swizzle_b32 v25, v3 offset:0x401f
	ds_swizzle_b32 v26, v4 offset:0x401f
	ds_swizzle_b32 v27, v5 offset:0x401f
	ds_swizzle_b32 v28, v6 offset:0x401f
	ds_swizzle_b32 v29, v7 offset:0x401f
	v_mul_f32_e32 v40, v40, v62
	v_mul_f32_e32 v41, v41, v63
	v_mul_f32_e32 v42, v42, v64
	v_mul_f32_e32 v43, v43, v65
	v_mul_f32_e32 v44, v44, v66
	v_mul_f32_e32 v45, v45, v67
	v_mul_f32_e32 v46, v46, v68
	v_mul_f32_e32 v47, v47, v69
	v_mul_f32_e32 v40, v40, v213
	v_mul_f32_e32 v41, v41, v213
	v_mul_f32_e32 v42, v42, v213
	v_mul_f32_e32 v43, v43, v213
	v_mul_f32_e32 v44, v44, v213
	v_mul_f32_e32 v45, v45, v213
	v_mul_f32_e32 v46, v46, v214
	v_mul_f32_e32 v47, v47, v214
	ds_swizzle_b32 v62, v40 offset:0x401f
	ds_swizzle_b32 v63, v41 offset:0x401f
	ds_swizzle_b32 v64, v42 offset:0x401f
	ds_swizzle_b32 v65, v43 offset:0x401f
	ds_swizzle_b32 v66, v44 offset:0x401f
	ds_swizzle_b32 v67, v45 offset:0x401f
	ds_swizzle_b32 v68, v46 offset:0x401f
	ds_swizzle_b32 v69, v47 offset:0x401f
	v_mul_f32_e32 v10, v10, v30
	v_mul_f32_e32 v11, v11, v30
	v_mul_f32_e32 v12, v12, v30
	v_mul_f32_e32 v13, v13, v30
	v_mul_f32_e32 v10, v10, v216
	v_mul_f32_e32 v11, v11, v217
	v_mul_f32_e32 v12, v12, v218
	v_mul_f32_e32 v13, v13, v219
	v_cvt_pk_bf16_f32 v8, v10, v11
	v_cvt_pk_bf16_f32 v9, v12, v13
	global_store_dwordx2 v223, v[8:9], s[64:65]
	v_mul_f32_e32 v15, v15, v31
	v_mul_f32_e32 v16, v16, v31
	v_mul_f32_e32 v15, v15, v220
	v_mul_f32_e32 v16, v16, v221
	v_cvt_pk_bf16_f32 v14, v15, v16
	global_store_dword v224, v14, s[66:67]
	v_mov_b32_dpp v32, v17 row_ror:8 row_mask:0xf bank_mask:0xf
	v_mul_f32_e32 v33, v17, v20
	v_xor_b32_e32 v32, v227, v32
	v_fmac_f32_e32 v33, v32, v21
	v_cvt_pk_bf16_f32 v38, v33, v33
	global_store_short v230, v38, s[68:69]
	s_add_u32 s68, s68, 0xcc000
	s_addc_u32 s69, s69, 0
	global_store_short v230, v38, s[68:69]
	s_add_u32 s68, s68, 0xcc000
	s_addc_u32 s69, s69, 0
	global_store_short v230, v38, s[68:69]
	v_mul_f32_e32 v50, v50, v70
	v_mul_f32_e32 v51, v51, v70
	v_mul_f32_e32 v52, v52, v70
	v_mul_f32_e32 v53, v53, v70
	v_mul_f32_e32 v50, v50, v216
	v_mul_f32_e32 v51, v51, v217
	v_mul_f32_e32 v52, v52, v218
	v_mul_f32_e32 v53, v53, v219
	v_cvt_pk_bf16_f32 v48, v50, v51
	v_cvt_pk_bf16_f32 v49, v52, v53
	global_store_dwordx2 v223, v[48:49], s[80:81]
	v_mul_f32_e32 v55, v55, v71
	v_mul_f32_e32 v56, v56, v71
	v_mul_f32_e32 v55, v55, v220
	v_mul_f32_e32 v56, v56, v221
	v_cvt_pk_bf16_f32 v54, v55, v56
	global_store_dword v224, v54, s[82:83]
	v_mov_b32_dpp v72, v57 row_ror:8 row_mask:0xf bank_mask:0xf
	v_mul_f32_e32 v73, v57, v60
	v_xor_b32_e32 v72, v227, v72
	v_fmac_f32_e32 v73, v72, v61
	v_cvt_pk_bf16_f32 v78, v73, v73
	global_store_short v230, v78, s[84:85]
	s_add_u32 s84, s84, 0xcc000
	s_addc_u32 s85, s85, 0
	global_store_short v230, v78, s[84:85]
	s_add_u32 s84, s84, 0xcc000
	s_addc_u32 s85, s85, 0
	global_store_short v230, v78, s[84:85]
	s_waitcnt lgkmcnt(8)
; DI bf16_t f2bf(float x) { return (bf16_t)(pack2(x, x) & 0xffffu); }
; DI float bf2f(bf16_t v) { return __uint_as_float(((unsigned)v) << 16); }
; DI void prep_row_store(const Params& p, int layer, int row, int lane, const PrepRow& R, float gq, float gk, float4 g4, float2 g2) {
;     ...
;   for (int hd = 0; hd < 8; ++hd) {
;     float xv = bf2f(R.hv[hd]);
;     float ss = wave_sum(xv * xv);
;     float y = xv * rsqrtf(ss * (1.0f / 64.f) + 1e-6f) * (hd < 6 ? gq : gk);
;     float pv = __shfl_xor(y, 16);
;     float o = y * cs_c + (upper ? pv : -pv) * cs_s;
;     if (hd < 6) Qg[((size_t)(b * 6 + hd) * NKEY + kp) * 64 + lane] = f2bf(o * qs);
;     else Kg[((size_t)(b * 2 + (hd - 6)) * NKEY + kp) * 64 + lane] = f2bf(o);
;   }
; DI void prep_rows(const Params& p, int layer) {
;     ...
;   for (int pr = gw; pr < (NTOK >> 1); pr += nw) {
;     const int row = pr * 2;
;     PrepRow Ra, Rb;
;     prep_row_load(p, row, U + (size_t)row * INP, lane, Ra);
;     prep_row_load(p, row + 1, U + (size_t)(row + 1) * INP, lane, Rb);
	v_xor_b32_e32 v22, v226, v22
	v_xor_b32_e32 v23, v226, v23
	v_xor_b32_e32 v24, v226, v24
	v_xor_b32_e32 v25, v226, v25
	v_xor_b32_e32 v26, v226, v26
	v_xor_b32_e32 v27, v226, v27
	v_xor_b32_e32 v28, v226, v28
	v_xor_b32_e32 v29, v226, v29
	v_mul_f32_e32 v0, v0, v18
	v_mul_f32_e32 v1, v1, v18
	v_mul_f32_e32 v2, v2, v18
	v_mul_f32_e32 v3, v3, v18
	v_mul_f32_e32 v4, v4, v18
	v_mul_f32_e32 v5, v5, v18
	v_mul_f32_e32 v6, v6, v18
	v_mul_f32_e32 v7, v7, v18
	v_fmac_f32_e32 v0, v22, v19
	v_fmac_f32_e32 v1, v23, v19
	v_fmac_f32_e32 v2, v24, v19
	v_fmac_f32_e32 v3, v25, v19
	v_fmac_f32_e32 v4, v26, v19
	v_fmac_f32_e32 v5, v27, v19
	v_fmac_f32_e32 v6, v28, v19
	v_fmac_f32_e32 v7, v29, v19
	v_mul_f32_e32 v0, v232, v0
	v_mul_f32_e32 v1, v232, v1
	v_mul_f32_e32 v2, v232, v2
	v_mul_f32_e32 v3, v232, v3
	v_mul_f32_e32 v4, v232, v4
	v_mul_f32_e32 v5, v232, v5
	v_cvt_pk_bf16_f32 v32, v0, v1
	v_cvt_pk_bf16_f32 v33, v2, v3
	v_cvt_pk_bf16_f32 v34, v4, v5
	v_cvt_pk_bf16_f32 v35, v6, v7
	global_store_short v222, v32, s[60:61]
	s_add_u32 s60, s60, 0x88000
	s_addc_u32 s61, s61, 0
	global_store_short_d16_hi v222, v32, s[60:61]
	s_add_u32 s60, s60, 0x88000
	s_addc_u32 s61, s61, 0
	global_store_short v222, v33, s[60:61]
	s_add_u32 s60, s60, 0x88000
	s_addc_u32 s61, s61, 0
	global_store_short_d16_hi v222, v33, s[60:61]
	s_add_u32 s60, s60, 0x88000
	s_addc_u32 s61, s61, 0
	global_store_short v222, v34, s[60:61]
	s_add_u32 s60, s60, 0x88000
	s_addc_u32 s61, s61, 0
	global_store_short_d16_hi v222, v34, s[60:61]
	global_store_short v222, v35, s[62:63]
	s_add_u32 s62, s62, 0x88000
	s_addc_u32 s63, s63, 0
	global_store_short_d16_hi v222, v35, s[62:63]
	s_waitcnt lgkmcnt(0)
	v_xor_b32_e32 v62, v226, v62
	v_xor_b32_e32 v63, v226, v63
	v_xor_b32_e32 v64, v226, v64
	v_xor_b32_e32 v65, v226, v65
	v_xor_b32_e32 v66, v226, v66
	v_xor_b32_e32 v67, v226, v67
	v_xor_b32_e32 v68, v226, v68
	v_xor_b32_e32 v69, v226, v69
	v_mul_f32_e32 v40, v40, v58
	v_mul_f32_e32 v41, v41, v58
	v_mul_f32_e32 v42, v42, v58
	v_mul_f32_e32 v43, v43, v58
	v_mul_f32_e32 v44, v44, v58
	v_mul_f32_e32 v45, v45, v58
	v_mul_f32_e32 v46, v46, v58
	v_mul_f32_e32 v47, v47, v58
	v_fmac_f32_e32 v40, v62, v59
	v_fmac_f32_e32 v41, v63, v59
	v_fmac_f32_e32 v42, v64, v59
	v_fmac_f32_e32 v43, v65, v59
	v_fmac_f32_e32 v44, v66, v59
	v_fmac_f32_e32 v45, v67, v59
	v_fmac_f32_e32 v46, v68, v59
	v_fmac_f32_e32 v47, v69, v59
	v_mul_f32_e32 v40, v232, v40
	v_mul_f32_e32 v41, v232, v41
	v_mul_f32_e32 v42, v232, v42
	v_mul_f32_e32 v43, v232, v43
	v_mul_f32_e32 v44, v232, v44
	v_mul_f32_e32 v45, v232, v45
	v_cvt_pk_bf16_f32 v72, v40, v41
	v_cvt_pk_bf16_f32 v73, v42, v43
	v_cvt_pk_bf16_f32 v74, v44, v45
	v_cvt_pk_bf16_f32 v75, v46, v47
	global_store_short v222, v72, s[76:77]
	s_add_u32 s76, s76, 0x88000
	s_addc_u32 s77, s77, 0
	global_store_short_d16_hi v222, v72, s[76:77]
	s_add_u32 s76, s76, 0x88000
	s_addc_u32 s77, s77, 0
	global_store_short v222, v73, s[76:77]
	s_add_u32 s76, s76, 0x88000
	s_addc_u32 s77, s77, 0
	global_store_short_d16_hi v222, v73, s[76:77]
	s_add_u32 s76, s76, 0x88000
	s_addc_u32 s77, s77, 0
	global_store_short v222, v74, s[76:77]
	s_add_u32 s76, s76, 0x88000
	s_addc_u32 s77, s77, 0
	global_store_short_d16_hi v222, v74, s[76:77]
	global_store_short v222, v75, s[78:79]
	s_add_u32 s78, s78, 0x88000
	s_addc_u32 s79, s79, 0
	global_store_short_d16_hi v222, v75, s[78:79]
	s_add_u32 s53, s53, s54
	s_cmpk_ge_u32 s53, 0x4400
	s_cbranch_scc1 .Lpp_done_2
	s_add_u32 s89, s53, s54
	s_min_u32 s55, s89, 0x43ff
	s_lshl_b32 s13, s55, 1
	s_mul_i32 s0, s13, 3840
	s_add_u32 s46, s24, s0
	s_addc_u32 s47, s25, 0
	global_load_ushort v0, v222, s[46:47] offset:1536
	global_load_ushort v1, v222, s[46:47] offset:1664
	global_load_ushort v2, v222, s[46:47] offset:1792
	global_load_ushort v3, v222, s[46:47] offset:1920
	global_load_ushort v4, v222, s[46:47] offset:2048
	global_load_ushort v5, v222, s[46:47] offset:2176
	global_load_ushort v6, v222, s[46:47] offset:2304
	global_load_ushort v7, v222, s[46:47] offset:2432
	global_load_dwordx2 v[8:9], v223, s[46:47] offset:2816
	global_load_dword v14, v224, s[46:47] offset:3328
	global_load_ushort v17, v225, s[46:47] offset:3584
	s_cmp_lt_u32 s13, 0x8000
	s_cbranch_scc0 .Lpp_ctx_15
	s_and_b32 s1, s13, 0xfff
	s_lshr_b32 s11, s1, 6
	s_and_b32 s12, s1, 63
	s_sub_u32 s12, s12, s11
	v_mov_b32_e32 v32, s12
	v_mul_lo_u32 v36, v32, v233
	v_add_u32_e32 v36, s11, v36
	v_lshl_add_u32 v36, v36, 7, v228
	v_mul_lo_u32 v37, v32, v184
	v_add_u32_e32 v37, s11, v37
	v_lshl_add_u32 v37, v37, 6, v229
	global_load_dwordx2 v[18:19], v36, s[28:29]
	global_load_dwordx2 v[20:21], v37, s[44:45]
	s_branch .Lpp_j_16

; DI void row_info(int row, int& b, int& kp) {
;   if (row < NLAT) { b = row >> 12; kp = CTX + (row & 4095); }
;   else { int r = row - NLAT; b = r >> 8; kp = r & 255; }
; }
.Lpp_j_18:
	s_lshl_b32 s70, s53, 1
	s_cmp_lt_u32 s70, 0x8000
	s_cbranch_scc0 .Lpp_cctx_19
	s_lshr_b32 s0, s70, 12
	s_and_b32 s10, s70, 0xfff
	s_add_u32 s10, s10, 256
	s_branch .Lpp_cj_20

; DI unsigned pack2(float lo, float hi) { f32x2_t v = {lo, hi}; bf16x2_t r = __builtin_convertvector(v, bf16x2_t); return __builtin_bit_cast(unsigned, r); }
; DI bf16_t f2bf(float x) { return (bf16_t)(pack2(x, x) & 0xffffu); }
; DI float bf2f(bf16_t v) { return __uint_as_float(((unsigned)v) << 16); }
; DI void prep_row_store(const Params& p, int layer, int row, int lane, const PrepRow& R, float gq, float gk, float4 g4, float2 g2) {
;   bf16_t* Qg = (bf16_t*)(p.ws + OFF_QG);
;   bf16_t* Kg = (bf16_t*)(p.ws + OFF_KG);
;   bf16_t* Km = (bf16_t*)(p.ws + OFF_KM);
;   bf16_t* MQN = (bf16_t*)(p.ws + OFF_MQN);
;   bf16_t* MKVN = (bf16_t*)(p.ws + OFF_MKVN);
;   const float qs = 0.125f * LOG2E;
;   int b, kp; row_info(row, b, kp);
;   const bool lat = row < NLAT;
;   const int s = row & 4095;
;   const float cs_c = R.cs.x, cs_s = R.cs.y;
;   const float2 tm = R.tm;
;   (void)s;
;   const bool upper = (lane >> 4) & 1;
; #pragma unroll
;   for (int hd = 0; hd < 8; ++hd) {
;     float xv = bf2f(R.hv[hd]);
;     float ss = wave_sum(xv * xv);
;     float y = xv * rsqrtf(ss * (1.0f / 64.f) + 1e-6f) * (hd < 6 ? gq : gk);
;     float pv = __shfl_xor(y, 16);
;     float o = y * cs_c + (upper ? pv : -pv) * cs_s;
;     if (hd < 6) Qg[((size_t)(b * 6 + hd) * NKEY + kp) * 64 + lane] = f2bf(o * qs);
;     else Kg[((size_t)(b * 2 + (hd - 6)) * NKEY + kp) * 64 + lane] = f2bf(o);
;   }
;   {
;     const uint2 w = R.mq;
;     float x0 = bf2f((bf16_t)(w.x & 0xffff)), x1 = bf2f((bf16_t)(w.x >> 16)), x2 = bf2f((bf16_t)(w.y & 0xffff)), x3 = bf2f((bf16_t)(w.y >> 16));
;     float ss = wave_sum(x0 * x0 + x1 * x1 + x2 * x2 + x3 * x3);
;     float rstd = rsqrtf(ss * (1.0f / 256.f) + 1e-6f);
;     uint2 o; o.x = pack2(x0 * rstd * g4.x, x1 * rstd * g4.y); o.y = pack2(x2 * rstd * g4.z, x3 * rstd * g4.w);
;     *(uint2*)(MQN + (size_t)row * 256 + lane * 4) = o;
;   }
;   {
;     const unsigned w = R.mkv;
;     float x0 = bf2f((bf16_t)(w & 0xffff)), x1 = bf2f((bf16_t)(w >> 16));
;     float ss = wave_sum(x0 * x0 + x1 * x1);
;     float rstd = rsqrtf(ss * (1.0f / 128.f) + 1e-6f);
;     *(unsigned*)(MKVN + (size_t)row * 128 + lane * 2) = pack2(x0 * rstd * g2.x, x1 * rstd * g2.y);
.Lpp_cj_22:
	s_mul_i32 s11, s0, 26112
	s_add_u32 s11, s11, s10
	s_lshl_b32 s12, s11, 7
	s_add_u32 s12, s12, 0x7f80000
	s_add_u32 s76, s24, s12
	s_addc_u32 s77, s25, 0
	s_mul_i32 s12, s11, 192
	s_add_u32 s12, s12, 0xd040000
	s_add_u32 s84, s24, s12
	s_addc_u32 s85, s25, 0
	s_mul_i32 s11, s0, 8704
	s_add_u32 s11, s11, s10
	s_lshl_b32 s12, s11, 7
	s_add_u32 s12, s12, 0x9900000
	s_add_u32 s78, s24, s12
	s_addc_u32 s79, s25, 0
	s_lshl_b32 s12, s86, 9
	s_add_u32 s12, s12, 0x11000000
	s_add_u32 s80, s24, s12
	s_addc_u32 s81, s25, 0
	s_lshl_b32 s12, s86, 8
	s_add_u32 s12, s12, 0x12100000
	s_add_u32 s82, s24, s12
	s_addc_u32 s83, s25, 0
	s_waitcnt vmcnt(39)
	v_lshlrev_b32_e32 v80, 16, v80
	v_lshlrev_b32_e32 v81, 16, v81
	v_lshlrev_b32_e32 v82, 16, v82
	v_lshlrev_b32_e32 v83, 16, v83
	v_lshlrev_b32_e32 v84, 16, v84
	v_lshlrev_b32_e32 v85, 16, v85
	v_lshlrev_b32_e32 v86, 16, v86
	v_lshlrev_b32_e32 v87, 16, v87
	v_lshlrev_b32_e32 v90, 16, v88
	v_and_b32_e32 v91, 0xffff0000, v88
	v_lshlrev_b32_e32 v92, 16, v89
	v_and_b32_e32 v93, 0xffff0000, v89
	v_lshlrev_b32_e32 v95, 16, v94
	v_and_b32_e32 v96, 0xffff0000, v94
	v_lshlrev_b32_e32 v97, 16, v97
	v_mul_f32_e32 v102, v80, v80
	v_mul_f32_e32 v103, v81, v81
	v_mul_f32_e32 v104, v82, v82
	v_mul_f32_e32 v105, v83, v83
	v_mul_f32_e32 v106, v84, v84
	v_mul_f32_e32 v107, v85, v85
	v_mul_f32_e32 v108, v86, v86
	v_mul_f32_e32 v109, v87, v87
	v_mul_f32_e32 v110, v90, v90
	v_fmac_f32_e32 v110, v91, v91
	v_fmac_f32_e32 v110, v92, v92
	v_fmac_f32_e32 v110, v93, v93
	v_mul_f32_e32 v111, v95, v95
	v_fmac_f32_e32 v111, v96, v96
	s_waitcnt vmcnt(26)
	v_lshlrev_b32_e32 v144, 16, v144
	v_lshlrev_b32_e32 v145, 16, v145
	v_lshlrev_b32_e32 v146, 16, v146
	v_lshlrev_b32_e32 v147, 16, v147
	v_lshlrev_b32_e32 v148, 16, v148
	v_lshlrev_b32_e32 v149, 16, v149
	v_lshlrev_b32_e32 v150, 16, v150
	v_lshlrev_b32_e32 v151, 16, v151
	v_lshlrev_b32_e32 v154, 16, v152
	v_and_b32_e32 v155, 0xffff0000, v152
	v_lshlrev_b32_e32 v156, 16, v153
	v_and_b32_e32 v157, 0xffff0000, v153
	v_lshlrev_b32_e32 v159, 16, v158
	v_and_b32_e32 v160, 0xffff0000, v158
	v_lshlrev_b32_e32 v161, 16, v161
	v_mul_f32_e32 v166, v144, v144
	v_mul_f32_e32 v167, v145, v145
	v_mul_f32_e32 v168, v146, v146
	v_mul_f32_e32 v169, v147, v147
	v_mul_f32_e32 v170, v148, v148
	v_mul_f32_e32 v171, v149, v149
	v_mul_f32_e32 v172, v150, v150
	v_mul_f32_e32 v173, v151, v151
	v_mul_f32_e32 v174, v154, v154
	v_fmac_f32_e32 v174, v155, v155
	v_fmac_f32_e32 v174, v156, v156
	v_fmac_f32_e32 v174, v157, v157
	v_mul_f32_e32 v175, v159, v159
	v_fmac_f32_e32 v175, v160, v160
	v_add_f32_dpp v102, v102, v102 quad_perm:[1,0,3,2] row_mask:0xf bank_mask:0xf
	v_add_f32_dpp v103, v103, v103 quad_perm:[1,0,3,2] row_mask:0xf bank_mask:0xf
	v_add_f32_dpp v104, v104, v104 quad_perm:[1,0,3,2] row_mask:0xf bank_mask:0xf
	v_add_f32_dpp v105, v105, v105 quad_perm:[1,0,3,2] row_mask:0xf bank_mask:0xf
	v_add_f32_dpp v106, v106, v106 quad_perm:[1,0,3,2] row_mask:0xf bank_mask:0xf
	v_add_f32_dpp v107, v107, v107 quad_perm:[1,0,3,2] row_mask:0xf bank_mask:0xf
	v_add_f32_dpp v108, v108, v108 quad_perm:[1,0,3,2] row_mask:0xf bank_mask:0xf
	v_add_f32_dpp v109, v109, v109 quad_perm:[1,0,3,2] row_mask:0xf bank_mask:0xf
	v_add_f32_dpp v110, v110, v110 quad_perm:[1,0,3,2] row_mask:0xf bank_mask:0xf
	v_add_f32_dpp v111, v111, v111 quad_perm:[1,0,3,2] row_mask:0xf bank_mask:0xf
	v_add_f32_dpp v166, v166, v166 quad_perm:[1,0,3,2] row_mask:0xf bank_mask:0xf
	v_add_f32_dpp v167, v167, v167 quad_perm:[1,0,3,2] row_mask:0xf bank_mask:0xf
	v_add_f32_dpp v168, v168, v168 quad_perm:[1,0,3,2] row_mask:0xf bank_mask:0xf
	v_add_f32_dpp v169, v169, v169 quad_perm:[1,0,3,2] row_mask:0xf bank_mask:0xf
	v_add_f32_dpp v170, v170, v170 quad_perm:[1,0,3,2] row_mask:0xf bank_mask:0xf
	v_add_f32_dpp v171, v171, v171 quad_perm:[1,0,3,2] row_mask:0xf bank_mask:0xf
	v_add_f32_dpp v172, v172, v172 quad_perm:[1,0,3,2] row_mask:0xf bank_mask:0xf
	v_add_f32_dpp v173, v173, v173 quad_perm:[1,0,3,2] row_mask:0xf bank_mask:0xf
	v_add_f32_dpp v174, v174, v174 quad_perm:[1,0,3,2] row_mask:0xf bank_mask:0xf
	v_add_f32_dpp v175, v175, v175 quad_perm:[1,0,3,2] row_mask:0xf bank_mask:0xf
	v_add_f32_dpp v102, v102, v102 quad_perm:[2,3,0,1] row_mask:0xf bank_mask:0xf
	v_add_f32_dpp v103, v103, v103 quad_perm:[2,3,0,1] row_mask:0xf bank_mask:0xf
	v_add_f32_dpp v104, v104, v104 quad_perm:[2,3,0,1] row_mask:0xf bank_mask:0xf
	v_add_f32_dpp v105, v105, v105 quad_perm:[2,3,0,1] row_mask:0xf bank_mask:0xf
	v_add_f32_dpp v106, v106, v106 quad_perm:[2,3,0,1] row_mask:0xf bank_mask:0xf
	v_add_f32_dpp v107, v107, v107 quad_perm:[2,3,0,1] row_mask:0xf bank_mask:0xf
	v_add_f32_dpp v108, v108, v108 quad_perm:[2,3,0,1] row_mask:0xf bank_mask:0xf
	v_add_f32_dpp v109, v109, v109 quad_perm:[2,3,0,1] row_mask:0xf bank_mask:0xf
	v_add_f32_dpp v110, v110, v110 quad_perm:[2,3,0,1] row_mask:0xf bank_mask:0xf
	v_add_f32_dpp v111, v111, v111 quad_perm:[2,3,0,1] row_mask:0xf bank_mask:0xf
	v_add_f32_dpp v166, v166, v166 quad_perm:[2,3,0,1] row_mask:0xf bank_mask:0xf
	v_add_f32_dpp v167, v167, v167 quad_perm:[2,3,0,1] row_mask:0xf bank_mask:0xf
	v_add_f32_dpp v168, v168, v168 quad_perm:[2,3,0,1] row_mask:0xf bank_mask:0xf
	v_add_f32_dpp v169, v169, v169 quad_perm:[2,3,0,1] row_mask:0xf bank_mask:0xf
	v_add_f32_dpp v170, v170, v170 quad_perm:[2,3,0,1] row_mask:0xf bank_mask:0xf
	v_add_f32_dpp v171, v171, v171 quad_perm:[2,3,0,1] row_mask:0xf bank_mask:0xf
	v_add_f32_dpp v172, v172, v172 quad_perm:[2,3,0,1] row_mask:0xf bank_mask:0xf
	v_add_f32_dpp v173, v173, v173 quad_perm:[2,3,0,1] row_mask:0xf bank_mask:0xf
	v_add_f32_dpp v174, v174, v174 quad_perm:[2,3,0,1] row_mask:0xf bank_mask:0xf
; DI unsigned pack2(float lo, float hi) { f32x2_t v = {lo, hi}; bf16x2_t r = __builtin_convertvector(v, bf16x2_t); return __builtin_bit_cast(unsigned, r); }
; DI bf16_t f2bf(float x) { return (bf16_t)(pack2(x, x) & 0xffffu); }
; DI float bf2f(bf16_t v) { return __uint_as_float(((unsigned)v) << 16); }
; DI float wave_sum(float v) {
; #pragma unroll
;   for (int o = 32; o > 0; o >>= 1) v += __shfl_xor(v, o);
;   return v;
; }
; DI void prep_row_store(const Params& p, int layer, int row, int lane, const PrepRow& R, float gq, float gk, float4 g4, float2 g2) {
;     ...
;     float ss = wave_sum(xv * xv);
;     float y = xv * rsqrtf(ss * (1.0f / 64.f) + 1e-6f) * (hd < 6 ? gq : gk);
;     float pv = __shfl_xor(y, 16);
;     float o = y * cs_c + (upper ? pv : -pv) * cs_s;
;     if (hd < 6) Qg[((size_t)(b * 6 + hd) * NKEY + kp) * 64 + lane] = f2bf(o * qs);
;     else Kg[((size_t)(b * 2 + (hd - 6)) * NKEY + kp) * 64 + lane] = f2bf(o);
;   }
;   {
;     const uint2 w = R.mq;
;     float x0 = bf2f((bf16_t)(w.x & 0xffff)), x1 = bf2f((bf16_t)(w.x >> 16)), x2 = bf2f((bf16_t)(w.y & 0xffff)), x3 = bf2f((bf16_t)(w.y >> 16));
;     float ss = wave_sum(x0 * x0 + x1 * x1 + x2 * x2 + x3 * x3);
;     float rstd = rsqrtf(ss * (1.0f / 256.f) + 1e-6f);
;     uint2 o; o.x = pack2(x0 * rstd * g4.x, x1 * rstd * g4.y); o.y = pack2(x2 * rstd * g4.z, x3 * rstd * g4.w);
;     *(uint2*)(MQN + (size_t)row * 256 + lane * 4) = o;
;   }
;   {
;     const unsigned w = R.mkv;
;     float x0 = bf2f((bf16_t)(w & 0xffff)), x1 = bf2f((bf16_t)(w >> 16));
;     float ss = wave_sum(x0 * x0 + x1 * x1);
	v_add_f32_dpp v175, v175, v175 quad_perm:[2,3,0,1] row_mask:0xf bank_mask:0xf
	v_add_f32_dpp v102, v102, v102 row_half_mirror row_mask:0xf bank_mask:0xf
	v_add_f32_dpp v103, v103, v103 row_half_mirror row_mask:0xf bank_mask:0xf
	v_add_f32_dpp v104, v104, v104 row_half_mirror row_mask:0xf bank_mask:0xf
	v_add_f32_dpp v105, v105, v105 row_half_mirror row_mask:0xf bank_mask:0xf
	v_add_f32_dpp v106, v106, v106 row_half_mirror row_mask:0xf bank_mask:0xf
	v_add_f32_dpp v107, v107, v107 row_half_mirror row_mask:0xf bank_mask:0xf
	v_add_f32_dpp v108, v108, v108 row_half_mirror row_mask:0xf bank_mask:0xf
	v_add_f32_dpp v109, v109, v109 row_half_mirror row_mask:0xf bank_mask:0xf
	v_add_f32_dpp v110, v110, v110 row_half_mirror row_mask:0xf bank_mask:0xf
	v_add_f32_dpp v111, v111, v111 row_half_mirror row_mask:0xf bank_mask:0xf
	v_add_f32_dpp v166, v166, v166 row_half_mirror row_mask:0xf bank_mask:0xf
	v_add_f32_dpp v167, v167, v167 row_half_mirror row_mask:0xf bank_mask:0xf
	v_add_f32_dpp v168, v168, v168 row_half_mirror row_mask:0xf bank_mask:0xf
	v_add_f32_dpp v169, v169, v169 row_half_mirror row_mask:0xf bank_mask:0xf
	v_add_f32_dpp v170, v170, v170 row_half_mirror row_mask:0xf bank_mask:0xf
	v_add_f32_dpp v171, v171, v171 row_half_mirror row_mask:0xf bank_mask:0xf
	v_add_f32_dpp v172, v172, v172 row_half_mirror row_mask:0xf bank_mask:0xf
	v_add_f32_dpp v173, v173, v173 row_half_mirror row_mask:0xf bank_mask:0xf
	v_add_f32_dpp v174, v174, v174 row_half_mirror row_mask:0xf bank_mask:0xf
	v_add_f32_dpp v175, v175, v175 row_half_mirror row_mask:0xf bank_mask:0xf
	v_add_f32_dpp v102, v102, v102 row_mirror row_mask:0xf bank_mask:0xf
	v_add_f32_dpp v103, v103, v103 row_mirror row_mask:0xf bank_mask:0xf
	v_add_f32_dpp v104, v104, v104 row_mirror row_mask:0xf bank_mask:0xf
	v_add_f32_dpp v105, v105, v105 row_mirror row_mask:0xf bank_mask:0xf
	v_add_f32_dpp v106, v106, v106 row_mirror row_mask:0xf bank_mask:0xf
	v_add_f32_dpp v107, v107, v107 row_mirror row_mask:0xf bank_mask:0xf
	v_add_f32_dpp v108, v108, v108 row_mirror row_mask:0xf bank_mask:0xf
	v_add_f32_dpp v109, v109, v109 row_mirror row_mask:0xf bank_mask:0xf
	v_add_f32_dpp v110, v110, v110 row_mirror row_mask:0xf bank_mask:0xf
	v_add_f32_dpp v111, v111, v111 row_mirror row_mask:0xf bank_mask:0xf
	v_add_f32_dpp v166, v166, v166 row_mirror row_mask:0xf bank_mask:0xf
	v_add_f32_dpp v167, v167, v167 row_mirror row_mask:0xf bank_mask:0xf
	v_add_f32_dpp v168, v168, v168 row_mirror row_mask:0xf bank_mask:0xf
	v_add_f32_dpp v169, v169, v169 row_mirror row_mask:0xf bank_mask:0xf
	v_add_f32_dpp v170, v170, v170 row_mirror row_mask:0xf bank_mask:0xf
	v_add_f32_dpp v171, v171, v171 row_mirror row_mask:0xf bank_mask:0xf
	v_add_f32_dpp v172, v172, v172 row_mirror row_mask:0xf bank_mask:0xf
	v_add_f32_dpp v173, v173, v173 row_mirror row_mask:0xf bank_mask:0xf
	v_add_f32_dpp v174, v174, v174 row_mirror row_mask:0xf bank_mask:0xf
	v_add_f32_dpp v175, v175, v175 row_mirror row_mask:0xf bank_mask:0xf
	s_nop 1
	v_readlane_b32 s90, v102, 0
	v_readlane_b32 s91, v102, 16
	v_readlane_b32 s72, v102, 32
	v_readlane_b32 s73, v102, 48
	s_nop 1
	v_mov_b32_e32 v102, s90
	v_add_f32_e32 v102, s91, v102
	v_add_f32_e32 v102, s72, v102
	v_add_f32_e32 v102, s73, v102
	v_readlane_b32 s90, v103, 0
	v_readlane_b32 s91, v103, 16
	v_readlane_b32 s72, v103, 32
	v_readlane_b32 s73, v103, 48
	s_nop 1
	v_mov_b32_e32 v103, s90
	v_add_f32_e32 v103, s91, v103
	v_add_f32_e32 v103, s72, v103
	v_add_f32_e32 v103, s73, v103
	v_readlane_b32 s90, v104, 0
	v_readlane_b32 s91, v104, 16
	v_readlane_b32 s72, v104, 32
	v_readlane_b32 s73, v104, 48
	s_nop 1
	v_mov_b32_e32 v104, s90
	v_add_f32_e32 v104, s91, v104
	v_add_f32_e32 v104, s72, v104
	v_add_f32_e32 v104, s73, v104
	v_readlane_b32 s90, v105, 0
	v_readlane_b32 s91, v105, 16
	v_readlane_b32 s72, v105, 32
	v_readlane_b32 s73, v105, 48
	s_nop 1
	v_mov_b32_e32 v105, s90
	v_add_f32_e32 v105, s91, v105
	v_add_f32_e32 v105, s72, v105
	v_add_f32_e32 v105, s73, v105
	v_readlane_b32 s90, v106, 0
	v_readlane_b32 s91, v106, 16
	v_readlane_b32 s72, v106, 32
	v_readlane_b32 s73, v106, 48
	s_nop 1
	v_mov_b32_e32 v106, s90
	v_add_f32_e32 v106, s91, v106
	v_add_f32_e32 v106, s72, v106
	v_add_f32_e32 v106, s73, v106
	v_readlane_b32 s90, v107, 0
	v_readlane_b32 s91, v107, 16
	v_readlane_b32 s72, v107, 32
	v_readlane_b32 s73, v107, 48
	s_nop 1
	v_mov_b32_e32 v107, s90
	v_add_f32_e32 v107, s91, v107
	v_add_f32_e32 v107, s72, v107
	v_add_f32_e32 v107, s73, v107
	v_readlane_b32 s90, v108, 0
	v_readlane_b32 s91, v108, 16
	v_readlane_b32 s72, v108, 32
	v_readlane_b32 s73, v108, 48
	s_nop 1
	v_mov_b32_e32 v108, s90
	v_add_f32_e32 v108, s91, v108
	v_add_f32_e32 v108, s72, v108
	v_add_f32_e32 v108, s73, v108
	v_readlane_b32 s90, v109, 0
	v_readlane_b32 s91, v109, 16
	v_readlane_b32 s72, v109, 32
	v_readlane_b32 s73, v109, 48
	s_nop 1
	v_mov_b32_e32 v109, s90
	v_add_f32_e32 v109, s91, v109
	v_add_f32_e32 v109, s72, v109
	v_add_f32_e32 v109, s73, v109
	v_readlane_b32 s90, v110, 0
	v_readlane_b32 s91, v110, 16
	v_readlane_b32 s72, v110, 32
	v_readlane_b32 s73, v110, 48
	s_nop 1
	v_mov_b32_e32 v110, s90
	v_add_f32_e32 v110, s91, v110
	v_add_f32_e32 v110, s72, v110
	v_add_f32_e32 v110, s73, v110
	v_readlane_b32 s90, v111, 0
	v_readlane_b32 s91, v111, 16
	v_readlane_b32 s72, v111, 32
	v_readlane_b32 s73, v111, 48
	s_nop 1
	v_mov_b32_e32 v111, s90
	v_add_f32_e32 v111, s91, v111
	v_add_f32_e32 v111, s72, v111
	v_add_f32_e32 v111, s73, v111
	v_readlane_b32 s90, v166, 0
	v_readlane_b32 s91, v166, 16
	v_readlane_b32 s72, v166, 32
	v_readlane_b32 s73, v166, 48
	s_nop 1
	v_mov_b32_e32 v166, s90
	v_add_f32_e32 v166, s91, v166
; DI unsigned pack2(float lo, float hi) { f32x2_t v = {lo, hi}; bf16x2_t r = __builtin_convertvector(v, bf16x2_t); return __builtin_bit_cast(unsigned, r); }
; DI bf16_t f2bf(float x) { return (bf16_t)(pack2(x, x) & 0xffffu); }
; DI float bf2f(bf16_t v) { return __uint_as_float(((unsigned)v) << 16); }
; DI void prep_row_store(const Params& p, int layer, int row, int lane, const PrepRow& R, float gq, float gk, float4 g4, float2 g2) {
;     ...
;   for (int hd = 0; hd < 8; ++hd) {
;     float xv = bf2f(R.hv[hd]);
;     float ss = wave_sum(xv * xv);
;     float y = xv * rsqrtf(ss * (1.0f / 64.f) + 1e-6f) * (hd < 6 ? gq : gk);
;     float pv = __shfl_xor(y, 16);
;     float o = y * cs_c + (upper ? pv : -pv) * cs_s;
;     if (hd < 6) Qg[((size_t)(b * 6 + hd) * NKEY + kp) * 64 + lane] = f2bf(o * qs);
;     else Kg[((size_t)(b * 2 + (hd - 6)) * NKEY + kp) * 64 + lane] = f2bf(o);
;   }
;   {
;     const uint2 w = R.mq;
;     float x0 = bf2f((bf16_t)(w.x & 0xffff)), x1 = bf2f((bf16_t)(w.x >> 16)), x2 = bf2f((bf16_t)(w.y & 0xffff)), x3 = bf2f((bf16_t)(w.y >> 16));
;     float ss = wave_sum(x0 * x0 + x1 * x1 + x2 * x2 + x3 * x3);
;     float rstd = rsqrtf(ss * (1.0f / 256.f) + 1e-6f);
;     uint2 o; o.x = pack2(x0 * rstd * g4.x, x1 * rstd * g4.y); o.y = pack2(x2 * rstd * g4.z, x3 * rstd * g4.w);
;     *(uint2*)(MQN + (size_t)row * 256 + lane * 4) = o;
;   }
;   {
;     const unsigned w = R.mkv;
;     float x0 = bf2f((bf16_t)(w & 0xffff)), x1 = bf2f((bf16_t)(w >> 16));
;     float ss = wave_sum(x0 * x0 + x1 * x1);
;     float rstd = rsqrtf(ss * (1.0f / 128.f) + 1e-6f);
;     *(unsigned*)(MKVN + (size_t)row * 128 + lane * 2) = pack2(x0 * rstd * g2.x, x1 * rstd * g2.y);
	v_add_f32_e32 v166, s72, v166
	v_add_f32_e32 v166, s73, v166
	v_readlane_b32 s90, v167, 0
	v_readlane_b32 s91, v167, 16
	v_readlane_b32 s72, v167, 32
	v_readlane_b32 s73, v167, 48
	s_nop 1
	v_mov_b32_e32 v167, s90
	v_add_f32_e32 v167, s91, v167
	v_add_f32_e32 v167, s72, v167
	v_add_f32_e32 v167, s73, v167
	v_readlane_b32 s90, v168, 0
	v_readlane_b32 s91, v168, 16
	v_readlane_b32 s72, v168, 32
	v_readlane_b32 s73, v168, 48
	s_nop 1
	v_mov_b32_e32 v168, s90
	v_add_f32_e32 v168, s91, v168
	v_add_f32_e32 v168, s72, v168
	v_add_f32_e32 v168, s73, v168
	v_readlane_b32 s90, v169, 0
	v_readlane_b32 s91, v169, 16
	v_readlane_b32 s72, v169, 32
	v_readlane_b32 s73, v169, 48
	s_nop 1
	v_mov_b32_e32 v169, s90
	v_add_f32_e32 v169, s91, v169
	v_add_f32_e32 v169, s72, v169
	v_add_f32_e32 v169, s73, v169
	v_readlane_b32 s90, v170, 0
	v_readlane_b32 s91, v170, 16
	v_readlane_b32 s72, v170, 32
	v_readlane_b32 s73, v170, 48
	s_nop 1
	v_mov_b32_e32 v170, s90
	v_add_f32_e32 v170, s91, v170
	v_add_f32_e32 v170, s72, v170
	v_add_f32_e32 v170, s73, v170
	v_readlane_b32 s90, v171, 0
	v_readlane_b32 s91, v171, 16
	v_readlane_b32 s72, v171, 32
	v_readlane_b32 s73, v171, 48
	s_nop 1
	v_mov_b32_e32 v171, s90
	v_add_f32_e32 v171, s91, v171
	v_add_f32_e32 v171, s72, v171
	v_add_f32_e32 v171, s73, v171
	v_readlane_b32 s90, v172, 0
	v_readlane_b32 s91, v172, 16
	v_readlane_b32 s72, v172, 32
	v_readlane_b32 s73, v172, 48
	s_nop 1
	v_mov_b32_e32 v172, s90
	v_add_f32_e32 v172, s91, v172
	v_add_f32_e32 v172, s72, v172
	v_add_f32_e32 v172, s73, v172
	v_readlane_b32 s90, v173, 0
	v_readlane_b32 s91, v173, 16
	v_readlane_b32 s72, v173, 32
	v_readlane_b32 s73, v173, 48
	s_nop 1
	v_mov_b32_e32 v173, s90
	v_add_f32_e32 v173, s91, v173
	v_add_f32_e32 v173, s72, v173
	v_add_f32_e32 v173, s73, v173
	v_readlane_b32 s90, v174, 0
	v_readlane_b32 s91, v174, 16
	v_readlane_b32 s72, v174, 32
	v_readlane_b32 s73, v174, 48
	s_nop 1
	v_mov_b32_e32 v174, s90
	v_add_f32_e32 v174, s91, v174
	v_add_f32_e32 v174, s72, v174
	v_add_f32_e32 v174, s73, v174
	v_readlane_b32 s90, v175, 0
	v_readlane_b32 s91, v175, 16
	v_readlane_b32 s72, v175, 32
	v_readlane_b32 s73, v175, 48
	s_nop 1
	v_mov_b32_e32 v175, s90
	v_add_f32_e32 v175, s91, v175
	v_add_f32_e32 v175, s72, v175
	v_add_f32_e32 v175, s73, v175
	s_mov_b32 s0, 0x3c800000
	s_mov_b32 s1, 0x3b800000
	s_mov_b32 s10, 0x3c000000
	v_fma_f32 v102, v102, s0, v231
	v_fma_f32 v103, v103, s0, v231
	v_fma_f32 v104, v104, s0, v231
	v_fma_f32 v105, v105, s0, v231
	v_fma_f32 v106, v106, s0, v231
	v_fma_f32 v107, v107, s0, v231
	v_fma_f32 v108, v108, s0, v231
	v_fma_f32 v109, v109, s0, v231
	v_fma_f32 v110, v110, s1, v231
	v_fma_f32 v111, v111, s10, v231
	v_rsq_f32_e32 v102, v102
	v_rsq_f32_e32 v103, v103
	v_rsq_f32_e32 v104, v104
	v_rsq_f32_e32 v105, v105
	v_rsq_f32_e32 v106, v106
	v_rsq_f32_e32 v107, v107
	v_rsq_f32_e32 v108, v108
	v_rsq_f32_e32 v109, v109
	v_rsq_f32_e32 v110, v110
	v_rsq_f32_e32 v111, v111
	v_fma_f32 v166, v166, s0, v231
	v_fma_f32 v167, v167, s0, v231
	v_fma_f32 v168, v168, s0, v231
	v_fma_f32 v169, v169, s0, v231
	v_fma_f32 v170, v170, s0, v231
	v_fma_f32 v171, v171, s0, v231
	v_fma_f32 v172, v172, s0, v231
	v_fma_f32 v173, v173, s0, v231
	v_fma_f32 v174, v174, s1, v231
	v_fma_f32 v175, v175, s10, v231
	v_rsq_f32_e32 v166, v166
	v_rsq_f32_e32 v167, v167
	v_rsq_f32_e32 v168, v168
	v_rsq_f32_e32 v169, v169
	v_rsq_f32_e32 v170, v170
	v_rsq_f32_e32 v171, v171
	v_rsq_f32_e32 v172, v172
	v_rsq_f32_e32 v173, v173
	v_rsq_f32_e32 v174, v174
	v_rsq_f32_e32 v175, v175
	v_mul_f32_e32 v80, v80, v102
	v_mul_f32_e32 v81, v81, v103
	v_mul_f32_e32 v82, v82, v104
	v_mul_f32_e32 v83, v83, v105
	v_mul_f32_e32 v84, v84, v106
	v_mul_f32_e32 v85, v85, v107
	v_mul_f32_e32 v86, v86, v108
	v_mul_f32_e32 v87, v87, v109
	v_mul_f32_e32 v80, v80, v213
	v_mul_f32_e32 v81, v81, v213
	v_mul_f32_e32 v82, v82, v213
	v_mul_f32_e32 v83, v83, v213
	v_mul_f32_e32 v84, v84, v213
	v_mul_f32_e32 v85, v85, v213
	v_mul_f32_e32 v86, v86, v214
	v_mul_f32_e32 v87, v87, v214
	ds_swizzle_b32 v102, v80 offset:0x401f
	ds_swizzle_b32 v103, v81 offset:0x401f
	ds_swizzle_b32 v104, v82 offset:0x401f
	ds_swizzle_b32 v105, v83 offset:0x401f
	ds_swizzle_b32 v106, v84 offset:0x401f
	ds_swizzle_b32 v107, v85 offset:0x401f
	ds_swizzle_b32 v108, v86 offset:0x401f
	ds_swizzle_b32 v109, v87 offset:0x401f
	v_mul_f32_e32 v144, v144, v166
	v_mul_f32_e32 v145, v145, v167
	v_mul_f32_e32 v146, v146, v168
	v_mul_f32_e32 v147, v147, v169
	v_mul_f32_e32 v148, v148, v170
	v_mul_f32_e32 v149, v149, v171
	v_mul_f32_e32 v150, v150, v172
	v_mul_f32_e32 v151, v151, v173
	v_mul_f32_e32 v144, v144, v213
	v_mul_f32_e32 v145, v145, v213
	v_mul_f32_e32 v146, v146, v213
	v_mul_f32_e32 v147, v147, v213
	v_mul_f32_e32 v148, v148, v213
	v_mul_f32_e32 v149, v149, v213
	v_mul_f32_e32 v150, v150, v214
	v_mul_f32_e32 v151, v151, v214
	ds_swizzle_b32 v166, v144 offset:0x401f
	ds_swizzle_b32 v167, v145 offset:0x401f
	ds_swizzle_b32 v168, v146 offset:0x401f
	ds_swizzle_b32 v169, v147 offset:0x401f
	ds_swizzle_b32 v170, v148 offset:0x401f
	ds_swizzle_b32 v171, v149 offset:0x401f
	ds_swizzle_b32 v172, v150 offset:0x401f
	ds_swizzle_b32 v173, v151 offset:0x401f
	v_mul_f32_e32 v90, v90, v110
	v_mul_f32_e32 v91, v91, v110
	v_mul_f32_e32 v92, v92, v110
	v_mul_f32_e32 v93, v93, v110
	v_mul_f32_e32 v90, v90, v216
	v_mul_f32_e32 v91, v91, v217
	v_mul_f32_e32 v92, v92, v218
	v_mul_f32_e32 v93, v93, v219
	v_cvt_pk_bf16_f32 v88, v90, v91
	v_cvt_pk_bf16_f32 v89, v92, v93
	global_store_dwordx2 v223, v[88:89], s[64:65]
	v_mul_f32_e32 v95, v95, v111
	v_mul_f32_e32 v96, v96, v111
	v_mul_f32_e32 v95, v95, v220
	v_mul_f32_e32 v96, v96, v221
; DI void prep_row_load(const Params& p, int row, const bf16_t* ur, int lane, PrepRow& R) {
;   {
;     const float2* csg = (const float2*)(p.ws + OFF_ROPEG);
;     const float2* csm = (const float2*)(p.ws + OFF_ROPEM);
;     const int s = row & 4095, d = lane & 31;
;     const int pg = (lane >> 5) ? (s & 63) : (s >> 6), pm = (d >> 4) ? (s & 63) : (s >> 6);
;     R.cs = csg[pg * 16 + (lane & 15)];
;     R.tm = csm[pm * 8 + (d & 7)];
;     if (row >= NLAT) { R.cs = make_float2(1.f, 0.f); R.tm = make_float2(1.f, 0.f); }
;   }
; #pragma unroll
;   for (int hd = 0; hd < 8; ++hd) R.hv[hd] = ur[768 + hd * 64 + lane];
;   R.mq = *(const uint2*)(ur + 1408 + lane * 4);
; DI void prep_row_store(const Params& p, int layer, int row, int lane, const PrepRow& R, float gq, float gk, float4 g4, float2 g2) {
;     ...
;   for (int hd = 0; hd < 8; ++hd) {
;     float xv = bf2f(R.hv[hd]);
;     float ss = wave_sum(xv * xv);
;     float y = xv * rsqrtf(ss * (1.0f / 64.f) + 1e-6f) * (hd < 6 ? gq : gk);
;     float pv = __shfl_xor(y, 16);
;     float o = y * cs_c + (upper ? pv : -pv) * cs_s;
;     if (hd < 6) Qg[((size_t)(b * 6 + hd) * NKEY + kp) * 64 + lane] = f2bf(o * qs);
;     else Kg[((size_t)(b * 2 + (hd - 6)) * NKEY + kp) * 64 + lane] = f2bf(o);
;   }
;   {
;     const uint2 w = R.mq;
;     float x0 = bf2f((bf16_t)(w.x & 0xffff)), x1 = bf2f((bf16_t)(w.x >> 16)), x2 = bf2f((bf16_t)(w.y & 0xffff)), x3 = bf2f((bf16_t)(w.y >> 16));
;     float ss = wave_sum(x0 * x0 + x1 * x1 + x2 * x2 + x3 * x3);
;     float rstd = rsqrtf(ss * (1.0f / 256.f) + 1e-6f);
;     uint2 o; o.x = pack2(x0 * rstd * g4.x, x1 * rstd * g4.y); o.y = pack2(x2 * rstd * g4.z, x3 * rstd * g4.w);
;     *(uint2*)(MQN + (size_t)row * 256 + lane * 4) = o;
;   }
;   {
;     const unsigned w = R.mkv;
;     float x0 = bf2f((bf16_t)(w & 0xffff)), x1 = bf2f((bf16_t)(w >> 16));
;     float ss = wave_sum(x0 * x0 + x1 * x1);
;     float rstd = rsqrtf(ss * (1.0f / 128.f) + 1e-6f);
;     *(unsigned*)(MKVN + (size_t)row * 128 + lane * 2) = pack2(x0 * rstd * g2.x, x1 * rstd * g2.y);
;   }
;   {
;     int d = lane & 31;
;     float xv = bf2f(R.kr);
;     float pv = __shfl_xor(xv, 8);
;     float o = lat ? (xv * tm.x + ((d & 8) ? pv : -pv) * tm.y) : xv;
;     bf16_t ob = f2bf(o);
;     int hb = (lane >> 5) * 3;
; #pragma unroll
;     for (int hh = 0; hh < 3; ++hh) Km[((size_t)(b * 6 + hb + hh) * NKEY + kp) * 96 + 64 + d] = ob;
;   }
; }
	v_cvt_pk_bf16_f32 v94, v95, v96
	global_store_dword v224, v94, s[66:67]
	v_mov_b32_dpp v112, v97 row_ror:8 row_mask:0xf bank_mask:0xf
	v_mul_f32_e32 v113, v97, v100
	v_xor_b32_e32 v112, v227, v112
	v_fmac_f32_e32 v113, v112, v101
	v_cvt_pk_bf16_f32 v118, v113, v113
	global_store_short v230, v118, s[68:69]
	s_add_u32 s68, s68, 0xcc000
	s_addc_u32 s69, s69, 0
	global_store_short v230, v118, s[68:69]
	s_add_u32 s68, s68, 0xcc000
	s_addc_u32 s69, s69, 0
	global_store_short v230, v118, s[68:69]
	v_mul_f32_e32 v154, v154, v174
	v_mul_f32_e32 v155, v155, v174
	v_mul_f32_e32 v156, v156, v174
	v_mul_f32_e32 v157, v157, v174
	v_mul_f32_e32 v154, v154, v216
	v_mul_f32_e32 v155, v155, v217
	v_mul_f32_e32 v156, v156, v218
	v_mul_f32_e32 v157, v157, v219
	v_cvt_pk_bf16_f32 v152, v154, v155
	v_cvt_pk_bf16_f32 v153, v156, v157
	global_store_dwordx2 v223, v[152:153], s[80:81]
	v_mul_f32_e32 v159, v159, v175
	v_mul_f32_e32 v160, v160, v175
	v_mul_f32_e32 v159, v159, v220
	v_mul_f32_e32 v160, v160, v221
	v_cvt_pk_bf16_f32 v158, v159, v160
	global_store_dword v224, v158, s[82:83]
	v_mov_b32_dpp v176, v161 row_ror:8 row_mask:0xf bank_mask:0xf
	v_mul_f32_e32 v177, v161, v164
	v_xor_b32_e32 v176, v227, v176
	v_fmac_f32_e32 v177, v176, v165
	v_cvt_pk_bf16_f32 v182, v177, v177
	global_store_short v230, v182, s[84:85]
	s_add_u32 s84, s84, 0xcc000
	s_addc_u32 s85, s85, 0
	global_store_short v230, v182, s[84:85]
	s_add_u32 s84, s84, 0xcc000
	s_addc_u32 s85, s85, 0
	global_store_short v230, v182, s[84:85]
	s_waitcnt lgkmcnt(8)
	v_xor_b32_e32 v102, v226, v102
	v_xor_b32_e32 v103, v226, v103
	v_xor_b32_e32 v104, v226, v104
	v_xor_b32_e32 v105, v226, v105
	v_xor_b32_e32 v106, v226, v106
	v_xor_b32_e32 v107, v226, v107
	v_xor_b32_e32 v108, v226, v108
	v_xor_b32_e32 v109, v226, v109
	v_mul_f32_e32 v80, v80, v98
	v_mul_f32_e32 v81, v81, v98
	v_mul_f32_e32 v82, v82, v98
	v_mul_f32_e32 v83, v83, v98
	v_mul_f32_e32 v84, v84, v98
	v_mul_f32_e32 v85, v85, v98
	v_mul_f32_e32 v86, v86, v98
	v_mul_f32_e32 v87, v87, v98
	v_fmac_f32_e32 v80, v102, v99
	v_fmac_f32_e32 v81, v103, v99
	v_fmac_f32_e32 v82, v104, v99
	v_fmac_f32_e32 v83, v105, v99
	v_fmac_f32_e32 v84, v106, v99
	v_fmac_f32_e32 v85, v107, v99
	v_fmac_f32_e32 v86, v108, v99
	v_fmac_f32_e32 v87, v109, v99
	v_mul_f32_e32 v80, v232, v80
	v_mul_f32_e32 v81, v232, v81
	v_mul_f32_e32 v82, v232, v82
	v_mul_f32_e32 v83, v232, v83
	v_mul_f32_e32 v84, v232, v84
	v_mul_f32_e32 v85, v232, v85
	v_cvt_pk_bf16_f32 v112, v80, v81
	v_cvt_pk_bf16_f32 v113, v82, v83
	v_cvt_pk_bf16_f32 v114, v84, v85
	v_cvt_pk_bf16_f32 v115, v86, v87
	global_store_short v222, v112, s[60:61]
	s_add_u32 s60, s60, 0x88000
	s_addc_u32 s61, s61, 0
	global_store_short_d16_hi v222, v112, s[60:61]
	s_add_u32 s60, s60, 0x88000
	s_addc_u32 s61, s61, 0
	global_store_short v222, v113, s[60:61]
	s_add_u32 s60, s60, 0x88000
	s_addc_u32 s61, s61, 0
	global_store_short_d16_hi v222, v113, s[60:61]
	s_add_u32 s60, s60, 0x88000
	s_addc_u32 s61, s61, 0
	global_store_short v222, v114, s[60:61]
	s_add_u32 s60, s60, 0x88000
	s_addc_u32 s61, s61, 0
	global_store_short_d16_hi v222, v114, s[60:61]
	global_store_short v222, v115, s[62:63]
	s_add_u32 s62, s62, 0x88000
	s_addc_u32 s63, s63, 0
	global_store_short_d16_hi v222, v115, s[62:63]
	s_waitcnt lgkmcnt(0)
	v_xor_b32_e32 v166, v226, v166
	v_xor_b32_e32 v167, v226, v167
	v_xor_b32_e32 v168, v226, v168
	v_xor_b32_e32 v169, v226, v169
	v_xor_b32_e32 v170, v226, v170
	v_xor_b32_e32 v171, v226, v171
	v_xor_b32_e32 v172, v226, v172
	v_xor_b32_e32 v173, v226, v173
	v_mul_f32_e32 v144, v144, v162
	v_mul_f32_e32 v145, v145, v162
	v_mul_f32_e32 v146, v146, v162
	v_mul_f32_e32 v147, v147, v162
	v_mul_f32_e32 v148, v148, v162
	v_mul_f32_e32 v149, v149, v162
	v_mul_f32_e32 v150, v150, v162
	v_mul_f32_e32 v151, v151, v162
	v_fmac_f32_e32 v144, v166, v163
	v_fmac_f32_e32 v145, v167, v163
	v_fmac_f32_e32 v146, v168, v163
	v_fmac_f32_e32 v147, v169, v163
	v_fmac_f32_e32 v148, v170, v163
	v_fmac_f32_e32 v149, v171, v163
	v_fmac_f32_e32 v150, v172, v163
	v_fmac_f32_e32 v151, v173, v163
	v_mul_f32_e32 v144, v232, v144
	v_mul_f32_e32 v145, v232, v145
	v_mul_f32_e32 v146, v232, v146
	v_mul_f32_e32 v147, v232, v147
	v_mul_f32_e32 v148, v232, v148
	v_mul_f32_e32 v149, v232, v149
	v_cvt_pk_bf16_f32 v176, v144, v145
	v_cvt_pk_bf16_f32 v177, v146, v147
	v_cvt_pk_bf16_f32 v178, v148, v149
	v_cvt_pk_bf16_f32 v179, v150, v151
	global_store_short v222, v176, s[76:77]
	s_add_u32 s76, s76, 0x88000
	s_addc_u32 s77, s77, 0
	global_store_short_d16_hi v222, v176, s[76:77]
	s_add_u32 s76, s76, 0x88000
	s_addc_u32 s77, s77, 0
	global_store_short v222, v177, s[76:77]
	s_add_u32 s76, s76, 0x88000
	s_addc_u32 s77, s77, 0
	global_store_short_d16_hi v222, v177, s[76:77]
	s_add_u32 s76, s76, 0x88000
	s_addc_u32 s77, s77, 0
	global_store_short v222, v178, s[76:77]
	s_add_u32 s76, s76, 0x88000
	s_addc_u32 s77, s77, 0
	global_store_short_d16_hi v222, v178, s[76:77]
	global_store_short v222, v179, s[78:79]
	s_add_u32 s78, s78, 0x88000
	s_addc_u32 s79, s79, 0
	global_store_short_d16_hi v222, v179, s[78:79]
	s_add_u32 s53, s53, s54
	s_cmpk_ge_u32 s53, 0x4400
	s_cbranch_scc1 .Lpp_done_2
	s_add_u32 s89, s53, s54
	s_min_u32 s55, s89, 0x43ff
	s_lshl_b32 s13, s55, 1
	s_mul_i32 s0, s13, 3840
	s_add_u32 s46, s24, s0
	s_addc_u32 s47, s25, 0
	global_load_ushort v80, v222, s[46:47] offset:1536
	global_load_ushort v81, v222, s[46:47] offset:1664
	global_load_ushort v82, v222, s[46:47] offset:1792
	global_load_ushort v83, v222, s[46:47] offset:1920
	global_load_ushort v84, v222, s[46:47] offset:2048
	global_load_ushort v85, v222, s[46:47] offset:2176
	global_load_ushort v86, v222, s[46:47] offset:2304
	global_load_ushort v87, v222, s[46:47] offset:2432
	global_load_dwordx2 v[88:89], v223, s[46:47] offset:2816
	global_load_dword v94, v224, s[46:47] offset:3328
	global_load_ushort v97, v225, s[46:47] offset:3584
	s_cmp_lt_u32 s13, 0x8000
	s_cbranch_scc0 .Lpp_ctx_23
	s_and_b32 s1, s13, 0xfff
	s_lshr_b32 s11, s1, 6
	s_and_b32 s12, s1, 63
	s_sub_u32 s12, s12, s11
	v_mov_b32_e32 v112, s12
	v_mul_lo_u32 v116, v112, v233
	v_add_u32_e32 v116, s11, v116
	v_lshl_add_u32 v116, v116, 7, v228
	v_mul_lo_u32 v117, v112, v184
	v_add_u32_e32 v117, s11, v117
	v_lshl_add_u32 v117, v117, 6, v229
	global_load_dwordx2 v[98:99], v116, s[28:29]
	global_load_dwordx2 v[100:101], v117, s[44:45]
	s_branch .Lpp_j_24

; DI void prep_rows(const Params& p, int layer) {
;     ...
;   for (int pr = gw; pr < (NTOK >> 1); pr += nw) {
;     const int row = pr * 2;
;     PrepRow Ra, Rb;
;     prep_row_load(p, row, U + (size_t)row * INP, lane, Ra);
;     prep_row_load(p, row + 1, U + (size_t)(row + 1) * INP, lane, Rb);
;     prep_row_store(p, layer, row, lane, Ra, gq, gk, g4, g2);
;     prep_row_store(p, layer, row + 1, lane, Rb, gq, gk, g4, g2);
;   }
; }
.Lpp_done_2:
	s_waitcnt vmcnt(0)
	v_readlane_b32 s52, v254, 0
	v_readlane_b32 s53, v254, 1
	v_readlane_b32 s54, v254, 2
	v_readlane_b32 s55, v254, 3
	v_readlane_b32 s56, v254, 4
	v_readlane_b32 s57, v254, 5
	v_readlane_b32 s58, v254, 6
	v_readlane_b32 s59, v254, 7
	v_readlane_b32 s60, v254, 8
	v_readlane_b32 s61, v254, 9
	v_readlane_b32 s62, v254, 10
	v_readlane_b32 s63, v254, 11
	v_readlane_b32 s64, v254, 12
	v_readlane_b32 s65, v254, 13
	v_readlane_b32 s66, v254, 14
	v_readlane_b32 s67, v254, 15
	v_readlane_b32 s68, v254, 16
	v_readlane_b32 s69, v254, 17
	v_readlane_b32 s70, v254, 18
	v_readlane_b32 s71, v254, 19
	v_readlane_b32 s72, v254, 20
	v_readlane_b32 s73, v254, 21
	v_readlane_b32 s74, v254, 22
	v_readlane_b32 s75, v254, 23
	v_readlane_b32 s76, v254, 24
	v_readlane_b32 s77, v254, 25
	v_readlane_b32 s78, v254, 26
	v_readlane_b32 s79, v254, 27
	v_readlane_b32 s80, v254, 28
	v_readlane_b32 s81, v254, 29
	v_readlane_b32 s82, v254, 30
	v_readlane_b32 s83, v254, 31
	v_readlane_b32 s84, v254, 32
	v_readlane_b32 s85, v254, 33
	v_readlane_b32 s86, v254, 34
	v_readlane_b32 s87, v254, 35
	v_readlane_b32 s88, v254, 36
	v_readlane_b32 s89, v254, 37
	v_readlane_b32 s90, v254, 38
	v_readlane_b32 s91, v254, 39
	s_nop 3
	s_branch .Lpp_ret
